# GEMM K-loop variant: DMA issue starts after the first group's fragment reads
# baseline (speedup 1.0000x reference)
.LBB0_212:
	s_add_i32 s1, s0, 0x10000
	s_and_b32 s11, s1, 0x10000
	s_waitcnt vmcnt(0)
	s_barrier
	s_and_b32 s0, s0, 0x10000
	s_add_i32 s0, s0, 0
	v_add_u32_e32 v155, s0, v153
	v_add_u32_e32 v164, v155, v151
	ds_read_b128 v[156:159], v164
	ds_read_b128 v[160:163], v164 offset:2048
	ds_read_b128 v[178:181], v164 offset:4096
	ds_read_b128 v[182:185], v164 offset:6144
	v_add_u32_e32 v249, v155, v150
	v_add_u32_e32 v164, s0, v154
	v_add_u32_e32 v165, v164, v151
	ds_read_b128 v[186:189], v165 offset:32768
	ds_read_b128 v[192:195], v165 offset:34816
	ds_read_b128 v[198:201], v165 offset:36864
	ds_read_b128 v[204:207], v165 offset:38912
	v_add_u32_e32 v248, v164, v150
	v_add_u32_e32 v251, s11, v152
	v_add_u32_e32 v240, 0x2000, v251
	v_readfirstlane_b32 s11, v251
	v_lshl_add_u64 v[174:175], v[144:145], 0, s[8:9]
	s_waitcnt lgkmcnt(0)
	v_mfma_f32_16x16x32_bf16 v[124:127], v[156:159], v[186:189], v[124:127]
	ds_read_b128 v[224:227], v165 offset:40960
	v_mfma_f32_16x16x32_bf16 v[120:123], v[156:159], v[192:195], v[120:123]
	ds_read_b128 v[228:231], v165 offset:43008
	v_mfma_f32_16x16x32_bf16 v[116:119], v[156:159], v[198:201], v[116:119]
	ds_read_b128 v[232:235], v165 offset:45056
	v_mfma_f32_16x16x32_bf16 v[112:115], v[156:159], v[204:207], v[112:115]
	ds_read_b128 v[236:239], v165 offset:47104
	v_mfma_f32_16x16x32_bf16 v[104:107], v[160:163], v[186:189], v[104:107]
	ds_read_b128 v[208:211], v249
	v_mfma_f32_16x16x32_bf16 v[96:99], v[160:163], v[192:195], v[96:99]
	ds_read_b128 v[212:215], v249 offset:2048
	v_mfma_f32_16x16x32_bf16 v[88:91], v[160:163], v[198:201], v[88:91]
	ds_read_b128 v[216:219], v249 offset:4096
	v_mfma_f32_16x16x32_bf16 v[80:83], v[160:163], v[204:207], v[80:83]
	ds_read_b128 v[220:223], v249 offset:6144
	v_mfma_f32_16x16x32_bf16 v[72:75], v[178:181], v[186:189], v[72:75]
	s_mov_b32 m0, s11
	v_readfirstlane_b32 s11, v240
	v_mfma_f32_16x16x32_bf16 v[64:67], v[178:181], v[192:195], v[64:67]
	v_add_u32_e32 v240, 0x4000, v251
	global_load_lds_dwordx4 v[174:175], off
	v_mfma_f32_16x16x32_bf16 v[56:59], v[178:181], v[198:201], v[56:59]
	v_lshl_add_u64 v[174:175], v[134:135], 0, s[8:9]
	s_mov_b32 m0, s11
	v_mfma_f32_16x16x32_bf16 v[48:51], v[178:181], v[204:207], v[48:51]
	v_readfirstlane_b32 s11, v240
	v_add_u32_e32 v240, 0x6000, v251
	v_mfma_f32_16x16x32_bf16 v[40:43], v[182:185], v[186:189], v[40:43]
	global_load_lds_dwordx4 v[174:175], off
	v_lshl_add_u64 v[174:175], v[132:133], 0, s[8:9]
	v_mfma_f32_16x16x32_bf16 v[32:35], v[182:185], v[192:195], v[32:35]
	s_mov_b32 m0, s11
	v_readfirstlane_b32 s11, v240
	v_mfma_f32_16x16x32_bf16 v[24:27], v[182:185], v[198:201], v[24:27]
	global_load_lds_dwordx4 v[174:175], off
	v_lshl_add_u64 v[174:175], v[130:131], 0, s[8:9]
	v_mfma_f32_16x16x32_bf16 v[16:19], v[182:185], v[204:207], v[16:19]
	s_mov_b32 m0, s11
	v_add_u32_e32 v250, 0x8000, v251
	s_waitcnt lgkmcnt(4)
	v_mfma_f32_16x16x32_bf16 v[100:103], v[156:159], v[224:227], v[100:103]
	global_load_lds_dwordx4 v[174:175], off
	v_lshl_add_u64 v[174:175], v[128:129], 0, s[8:9]
	v_mfma_f32_16x16x32_bf16 v[92:95], v[156:159], v[228:231], v[92:95]
	v_readfirstlane_b32 s11, v250
	v_add_u32_e32 v250, 0xa000, v251
	v_mfma_f32_16x16x32_bf16 v[84:87], v[156:159], v[232:235], v[84:87]
	ds_read_b128 v[186:189], v248 offset:32768
	v_lshl_add_u64 v[240:241], v[174:175], 0, s[66:67]
	s_mov_b32 m0, s11
	v_mfma_f32_16x16x32_bf16 v[76:79], v[156:159], v[236:239], v[76:79]
	ds_read_b128 v[192:195], v248 offset:34816
	s_mov_b64 s[12:13], 0x22080
	v_readfirstlane_b32 s11, v250
	v_mfma_f32_16x16x32_bf16 v[68:71], v[160:163], v[224:227], v[68:71]
	ds_read_b128 v[198:201], v248 offset:36864
	v_add_u32_e32 v250, 0xc000, v251
	global_load_lds_dwordx4 v[240:241], off
	v_mfma_f32_16x16x32_bf16 v[60:63], v[160:163], v[228:231], v[60:63]
	ds_read_b128 v[204:207], v248 offset:38912
	v_lshl_add_u64 v[240:241], v[174:175], 0, s[12:13]
	s_mov_b32 m0, s11
	v_mfma_f32_16x16x32_bf16 v[52:55], v[160:163], v[232:235], v[52:55]
	s_mov_b64 s[12:13], 0x44080
	v_readfirstlane_b32 s11, v250
	v_mfma_f32_16x16x32_bf16 v[44:47], v[160:163], v[236:239], v[44:47]
	v_add_u32_e32 v251, 0xe000, v251
	global_load_lds_dwordx4 v[240:241], off
	v_mfma_f32_16x16x32_bf16 v[36:39], v[178:181], v[224:227], v[36:39]
	v_lshl_add_u64 v[240:241], v[174:175], 0, s[12:13]
	s_mov_b32 m0, s11
	v_mfma_f32_16x16x32_bf16 v[28:31], v[178:181], v[228:231], v[28:31]
	s_mov_b64 s[12:13], 0x66080
	v_readfirstlane_b32 s11, v251
	v_mfma_f32_16x16x32_bf16 v[20:23], v[178:181], v[232:235], v[20:23]
	global_load_lds_dwordx4 v[240:241], off
	v_lshl_add_u64 v[174:175], v[174:175], 0, s[12:13]
	v_mfma_f32_16x16x32_bf16 v[12:15], v[178:181], v[236:239], v[12:15]
	s_mov_b32 m0, s11
	global_load_lds_dwordx4 v[174:175], off
	v_mfma_f32_16x16x32_bf16 v[8:11], v[182:185], v[224:227], v[8:11]
	v_mfma_f32_16x16x32_bf16 v[4:7], v[182:185], v[228:231], v[4:7]
	v_mfma_f32_16x16x32_bf16 v[0:3], v[182:185], v[232:235], v[0:3]
	v_mfma_f32_16x16x32_bf16 v[108:111], v[182:185], v[236:239], v[108:111]
	s_waitcnt lgkmcnt(0)
	v_mfma_f32_16x16x32_bf16 v[124:127], v[208:211], v[186:189], v[124:127]
	ds_read_b128 v[224:227], v248 offset:40960
	v_mfma_f32_16x16x32_bf16 v[120:123], v[208:211], v[192:195], v[120:123]
	ds_read_b128 v[228:231], v248 offset:43008
	v_mfma_f32_16x16x32_bf16 v[116:119], v[208:211], v[198:201], v[116:119]
	ds_read_b128 v[232:235], v248 offset:45056
	v_mfma_f32_16x16x32_bf16 v[112:115], v[208:211], v[204:207], v[112:115]
	ds_read_b128 v[236:239], v248 offset:47104
	v_mfma_f32_16x16x32_bf16 v[104:107], v[212:215], v[186:189], v[104:107]
	v_mfma_f32_16x16x32_bf16 v[96:99], v[212:215], v[192:195], v[96:99]
	v_mfma_f32_16x16x32_bf16 v[88:91], v[212:215], v[198:201], v[88:91]
	v_mfma_f32_16x16x32_bf16 v[80:83], v[212:215], v[204:207], v[80:83]
	v_mfma_f32_16x16x32_bf16 v[72:75], v[216:219], v[186:189], v[72:75]
	v_mfma_f32_16x16x32_bf16 v[64:67], v[216:219], v[192:195], v[64:67]
	v_mfma_f32_16x16x32_bf16 v[56:59], v[216:219], v[198:201], v[56:59]
	v_mfma_f32_16x16x32_bf16 v[48:51], v[216:219], v[204:207], v[48:51]
	v_mfma_f32_16x16x32_bf16 v[40:43], v[220:223], v[186:189], v[40:43]
	v_mfma_f32_16x16x32_bf16 v[32:35], v[220:223], v[192:195], v[32:35]
	v_mfma_f32_16x16x32_bf16 v[24:27], v[220:223], v[198:201], v[24:27]
	v_mfma_f32_16x16x32_bf16 v[16:19], v[220:223], v[204:207], v[16:19]
	s_waitcnt lgkmcnt(0)
	v_mfma_f32_16x16x32_bf16 v[100:103], v[208:211], v[224:227], v[100:103]
	v_mfma_f32_16x16x32_bf16 v[92:95], v[208:211], v[228:231], v[92:95]
	v_mfma_f32_16x16x32_bf16 v[84:87], v[208:211], v[232:235], v[84:87]
	v_mfma_f32_16x16x32_bf16 v[76:79], v[208:211], v[236:239], v[76:79]
	v_mfma_f32_16x16x32_bf16 v[68:71], v[212:215], v[224:227], v[68:71]
	v_mfma_f32_16x16x32_bf16 v[60:63], v[212:215], v[228:231], v[60:63]
	v_mfma_f32_16x16x32_bf16 v[52:55], v[212:215], v[232:235], v[52:55]
	v_mfma_f32_16x16x32_bf16 v[44:47], v[212:215], v[236:239], v[44:47]
	v_mfma_f32_16x16x32_bf16 v[36:39], v[216:219], v[224:227], v[36:39]
	v_mfma_f32_16x16x32_bf16 v[28:31], v[216:219], v[228:231], v[28:31]
	v_mfma_f32_16x16x32_bf16 v[20:23], v[216:219], v[232:235], v[20:23]
	v_mfma_f32_16x16x32_bf16 v[12:15], v[216:219], v[236:239], v[12:15]
	s_add_u32 s8, s8, 0x80
	s_addc_u32 s9, s9, 0
	s_cmpk_eq_i32 s8, 0x780
	s_mov_b32 s0, s1
	v_mfma_f32_16x16x32_bf16 v[8:11], v[220:223], v[224:227], v[8:11]
	v_mfma_f32_16x16x32_bf16 v[4:7], v[220:223], v[228:231], v[4:7]
	v_mfma_f32_16x16x32_bf16 v[0:3], v[220:223], v[232:235], v[0:3]
	v_mfma_f32_16x16x32_bf16 v[108:111], v[220:223], v[236:239], v[108:111]
	s_cbranch_scc0 .LBB0_212
	s_add_i32 s0, 0, 0x10000
	v_add_u32_e32 v144, s0, v154
	v_add_u32_e32 v162, s0, v153
	v_add_u32_e32 v145, v144, v151
	v_add_u32_e32 v151, v162, v151
	s_waitcnt vmcnt(0)
	s_barrier
	ds_read_b128 v[128:131], v145 offset:38912
	ds_read_b128 v[132:135], v145 offset:36864
	ds_read_b128 v[154:157], v145 offset:34816
	ds_read_b128 v[158:161], v145 offset:32768
	ds_read_b128 v[178:181], v151 offset:6144
	ds_read_b128 v[182:185], v151 offset:4096
	ds_read_b128 v[186:189], v151 offset:2048
	ds_read_b128 v[204:207], v151
	s_waitcnt lgkmcnt(0)
	v_mfma_f32_16x16x32_bf16 v[124:127], v[204:207], v[158:161], v[124:127]
	v_mfma_f32_16x16x32_bf16 v[120:123], v[204:207], v[154:157], v[120:123]
	v_mfma_f32_16x16x32_bf16 v[116:119], v[204:207], v[132:135], v[116:119]
	v_mfma_f32_16x16x32_bf16 v[112:115], v[204:207], v[128:131], v[112:115]
	v_mfma_f32_16x16x32_bf16 v[104:107], v[186:189], v[158:161], v[104:107]
	v_mfma_f32_16x16x32_bf16 v[72:75], v[182:185], v[158:161], v[72:75]
	v_mfma_f32_16x16x32_bf16 v[64:67], v[182:185], v[154:157], v[64:67]
	v_mfma_f32_16x16x32_bf16 v[56:59], v[182:185], v[132:135], v[56:59]
	v_mfma_f32_16x16x32_bf16 v[48:51], v[182:185], v[128:131], v[48:51]
	v_mfma_f32_16x16x32_bf16 v[208:211], v[186:189], v[154:157], v[96:99]
	v_mfma_f32_16x16x32_bf16 v[212:215], v[186:189], v[132:135], v[88:91]
	v_mfma_f32_16x16x32_bf16 v[216:219], v[186:189], v[128:131], v[80:83]
	v_mfma_f32_16x16x32_bf16 v[158:161], v[178:181], v[158:161], v[40:43]
	v_mfma_f32_16x16x32_bf16 v[152:155], v[178:181], v[154:157], v[32:35]
	v_mfma_f32_16x16x32_bf16 v[132:135], v[178:181], v[132:135], v[24:27]
	v_mfma_f32_16x16x32_bf16 v[128:131], v[178:181], v[128:131], v[16:19]
	s_nop 2
	ds_read_b128 v[16:19], v145 offset:40960
	ds_read_b128 v[24:27], v145 offset:43008
	ds_read_b128 v[32:35], v145 offset:45056
	ds_read_b128 v[40:43], v145 offset:47104
	s_waitcnt lgkmcnt(0)
	v_mfma_f32_16x16x32_bf16 v[100:103], v[204:207], v[16:19], v[100:103]
	v_mfma_f32_16x16x32_bf16 v[92:95], v[204:207], v[24:27], v[92:95]
	v_mfma_f32_16x16x32_bf16 v[220:223], v[204:207], v[32:35], v[84:87]
	v_mfma_f32_16x16x32_bf16 v[76:79], v[204:207], v[40:43], v[76:79]
	v_mfma_f32_16x16x32_bf16 v[68:71], v[186:189], v[16:19], v[68:71]
	v_mfma_f32_16x16x32_bf16 v[60:63], v[186:189], v[24:27], v[60:63]
	v_mfma_f32_16x16x32_bf16 v[204:207], v[186:189], v[32:35], v[52:55]
	v_mfma_f32_16x16x32_bf16 v[44:47], v[186:189], v[40:43], v[44:47]
	v_mfma_f32_16x16x32_bf16 v[186:189], v[182:185], v[16:19], v[36:39]
	v_mfma_f32_16x16x32_bf16 v[224:227], v[182:185], v[24:27], v[28:31]
	v_mfma_f32_16x16x32_bf16 v[228:231], v[182:185], v[32:35], v[20:23]
	v_mfma_f32_16x16x32_bf16 v[182:185], v[182:185], v[40:43], v[12:15]
	v_mfma_f32_16x16x32_bf16 v[232:235], v[178:181], v[16:19], v[8:11]
	v_mfma_f32_16x16x32_bf16 v[236:239], v[178:181], v[24:27], v[4:7]
	v_mfma_f32_16x16x32_bf16 v[240:243], v[178:181], v[32:35], v[0:3]
	v_mfma_f32_16x16x32_bf16 v[244:247], v[178:181], v[40:43], v[108:111]
	s_nop 1
	v_add_u32_e32 v0, v162, v150
	v_add_u32_e32 v144, v144, v150
	ds_read_b128 v[108:111], v0
	ds_read_b128 v[178:181], v0 offset:2048
	ds_read_b128 v[248:251], v0 offset:4096
	ds_read_b128 v[192:195], v0 offset:6144
	ds_read_b128 v[0:3], v144 offset:32768
	ds_read_b128 v[4:7], v144 offset:34816
	ds_read_b128 v[198:201], v144 offset:36864
	ds_read_b128 v[162:165], v144 offset:38912
	s_waitcnt lgkmcnt(0)
	v_mfma_f32_16x16x32_bf16 v[88:91], v[108:111], v[0:3], v[124:127]
	v_mfma_f32_16x16x32_bf16 v[96:99], v[108:111], v[4:7], v[120:123]
	v_mfma_f32_16x16x32_bf16 v[80:83], v[108:111], v[198:201], v[116:119]
	v_mfma_f32_16x16x32_bf16 v[84:87], v[108:111], v[162:165], v[112:115]
	v_mfma_f32_16x16x32_bf16 v[40:43], v[178:181], v[0:3], v[104:107]
	v_mfma_f32_16x16x32_bf16 v[52:55], v[178:181], v[4:7], v[208:211]
	v_mfma_f32_16x16x32_bf16 v[32:35], v[178:181], v[198:201], v[212:215]
	v_mfma_f32_16x16x32_bf16 v[36:39], v[178:181], v[162:165], v[216:219]
	v_mfma_f32_16x16x32_bf16 v[24:27], v[248:251], v[0:3], v[72:75]
	v_mfma_f32_16x16x32_bf16 v[28:31], v[248:251], v[4:7], v[64:67]
	v_mfma_f32_16x16x32_bf16 v[16:19], v[248:251], v[198:201], v[56:59]
	v_mfma_f32_16x16x32_bf16 v[20:23], v[248:251], v[162:165], v[48:51]
	v_mfma_f32_16x16x32_bf16 v[8:11], v[192:195], v[0:3], v[158:161]
	v_mfma_f32_16x16x32_bf16 v[12:15], v[192:195], v[4:7], v[152:155]
	v_mfma_f32_16x16x32_bf16 v[0:3], v[192:195], v[198:201], v[132:135]
	v_mfma_f32_16x16x32_bf16 v[4:7], v[192:195], v[162:165], v[128:131]
	ds_read_b128 v[48:51], v144 offset:40960
	ds_read_b128 v[64:67], v144 offset:43008
	s_nop 0
	ds_read_b128 v[128:131], v144 offset:45056
	ds_read_b128 v[132:135], v144 offset:47104
	s_waitcnt lgkmcnt(0)
	v_mfma_f32_16x16x32_bf16 v[104:107], v[178:181], v[48:51], v[68:71]
	v_cmp_ne_u32_e64 s[8:9], 0, v146
	v_cmp_eq_u32_e32 vcc, 0, v146
	s_waitcnt vmcnt(0)
	v_lshl_or_b32 v68, v148, 2, v149
	v_lshl_add_u32 v69, v147, 2, 0
	v_mfma_f32_16x16x32_bf16 v[120:123], v[108:111], v[48:51], v[100:103]
	s_barrier
	v_mfma_f32_16x16x32_bf16 v[124:127], v[108:111], v[64:67], v[92:95]
	v_mfma_f32_16x16x32_bf16 v[112:115], v[108:111], v[128:131], v[220:223]
	v_mfma_f32_16x16x32_bf16 v[116:119], v[108:111], v[132:135], v[76:79]
	v_mfma_f32_16x16x32_bf16 v[108:111], v[178:181], v[64:67], v[60:63]
	v_mfma_f32_16x16x32_bf16 v[92:95], v[178:181], v[128:131], v[204:207]
	v_mfma_f32_16x16x32_bf16 v[100:103], v[178:181], v[132:135], v[44:47]
	v_mfma_f32_16x16x32_bf16 v[56:59], v[248:251], v[48:51], v[186:189]
	v_mfma_f32_16x16x32_bf16 v[60:63], v[248:251], v[64:67], v[224:227]
	v_mfma_f32_16x16x32_bf16 v[44:47], v[248:251], v[128:131], v[228:231]
	v_mfma_f32_16x16x32_bf16 v[72:75], v[248:251], v[132:135], v[182:185]
	v_mfma_f32_16x16x32_bf16 v[48:51], v[192:195], v[48:51], v[232:235]
	s_nop 1
	v_lshl_add_u32 v182, v68, 9, v69
	v_add_u32_e32 v183, 0x400, v182
	v_add_u32_e32 v181, 0x2000, v182
	v_mfma_f32_16x16x32_bf16 v[64:67], v[192:195], v[64:67], v[236:239]
	v_add_u32_e32 v180, 0x2400, v182
	v_add_u32_e32 v179, 0x4000, v182
	v_add_u32_e32 v178, 0x4400, v182
	v_mfma_f32_16x16x32_bf16 v[68:71], v[192:195], v[128:131], v[240:243]
	v_add_u32_e32 v175, 0x6000, v182
	v_add_u32_e32 v174, 0x6400, v182
	v_mfma_f32_16x16x32_bf16 v[76:79], v[192:195], v[132:135], v[244:247]
	s_and_saveexec_b64 s[0:1], vcc
	s_cbranch_execz .LBB0_215
	ds_write2_b32 v182, v88, v96 offset1:16
	ds_write2_b32 v182, v89, v97 offset0:128 offset1:144
	ds_write2_b32 v183, v90, v98 offset1:16
	ds_write2_b32 v183, v91, v99 offset0:128 offset1:144
	ds_write2_b32 v182, v80, v84 offset0:32 offset1:48
	ds_write2_b32 v182, v81, v85 offset0:160 offset1:176
	ds_write2_b32 v183, v82, v86 offset0:32 offset1:48
	ds_write2_b32 v183, v83, v87 offset0:160 offset1:176
	ds_write2_b32 v182, v120, v124 offset0:64 offset1:80
	ds_write2_b32 v182, v121, v125 offset0:192 offset1:208
	ds_write2_b32 v183, v122, v126 offset0:64 offset1:80
	ds_write2_b32 v183, v123, v127 offset0:192 offset1:208
	ds_write2_b32 v182, v112, v116 offset0:96 offset1:112
	ds_write2_b32 v182, v113, v117 offset0:224 offset1:240
	ds_write2_b32 v183, v114, v118 offset0:96 offset1:112
	ds_write2_b32 v183, v115, v119 offset0:224 offset1:240
	ds_write2_b32 v181, v40, v52 offset1:16
	ds_write2_b32 v181, v41, v53 offset0:128 offset1:144
	ds_write2_b32 v180, v42, v54 offset1:16
	ds_write2_b32 v180, v43, v55 offset0:128 offset1:144
	ds_write2_b32 v181, v32, v36 offset0:32 offset1:48
	ds_write2_b32 v181, v33, v37 offset0:160 offset1:176
	ds_write2_b32 v180, v34, v38 offset0:32 offset1:48
	ds_write2_b32 v180, v35, v39 offset0:160 offset1:176
	ds_write2_b32 v181, v104, v108 offset0:64 offset1:80
	ds_write2_b32 v181, v105, v109 offset0:192 offset1:208
	ds_write2_b32 v180, v106, v110 offset0:64 offset1:80
	ds_write2_b32 v180, v107, v111 offset0:192 offset1:208
	ds_write2_b32 v181, v92, v100 offset0:96 offset1:112
	ds_write2_b32 v181, v93, v101 offset0:224 offset1:240
	ds_write2_b32 v180, v94, v102 offset0:96 offset1:112
	ds_write2_b32 v180, v95, v103 offset0:224 offset1:240
	ds_write2_b32 v179, v24, v28 offset1:16
	ds_write2_b32 v179, v25, v29 offset0:128 offset1:144
	ds_write2_b32 v178, v26, v30 offset1:16
	ds_write2_b32 v178, v27, v31 offset0:128 offset1:144
	ds_write2_b32 v179, v16, v20 offset0:32 offset1:48
	ds_write2_b32 v179, v17, v21 offset0:160 offset1:176
	ds_write2_b32 v178, v18, v22 offset0:32 offset1:48
	ds_write2_b32 v178, v19, v23 offset0:160 offset1:176
	ds_write2_b32 v179, v56, v60 offset0:64 offset1:80
	ds_write2_b32 v179, v57, v61 offset0:192 offset1:208
	ds_write2_b32 v178, v58, v62 offset0:64 offset1:80
	ds_write2_b32 v178, v59, v63 offset0:192 offset1:208
	ds_write2_b32 v179, v44, v72 offset0:96 offset1:112
	ds_write2_b32 v179, v45, v73 offset0:224 offset1:240
	ds_write2_b32 v178, v46, v74 offset0:96 offset1:112
	ds_write2_b32 v178, v47, v75 offset0:224 offset1:240
	ds_write2_b32 v175, v8, v12 offset1:16
	ds_write2_b32 v175, v9, v13 offset0:128 offset1:144
	ds_write2_b32 v174, v10, v14 offset1:16
	ds_write2_b32 v174, v11, v15 offset0:128 offset1:144
	ds_write2_b32 v175, v0, v4 offset0:32 offset1:48
	ds_write2_b32 v175, v1, v5 offset0:160 offset1:176
	ds_write2_b32 v174, v2, v6 offset0:32 offset1:48
	ds_write2_b32 v174, v3, v7 offset0:160 offset1:176
	ds_write2_b32 v175, v48, v64 offset0:64 offset1:80
	ds_write2_b32 v175, v49, v65 offset0:192 offset1:208
	ds_write2_b32 v174, v50, v66 offset0:64 offset1:80
	ds_write2_b32 v174, v51, v67 offset0:192 offset1:208
	ds_write2_b32 v175, v68, v76 offset0:96 offset1:112
	ds_write2_b32 v175, v69, v77 offset0:224 offset1:240
	ds_write2_b32 v174, v70, v78 offset0:96 offset1:112
	ds_write2_b32 v174, v71, v79 offset0:224 offset1:240

.LBB0_659:
	s_add_i32 s1, s0, 0x10000
	s_and_b32 s11, s1, 0x10000
	s_waitcnt vmcnt(0)
	s_barrier
	s_and_b32 s0, s0, 0x10000
	s_add_i32 s0, s0, 0
	v_add_u32_e32 v151, s0, v149
	v_add_u32_e32 v164, v151, v147
	ds_read_b128 v[152:155], v164
	ds_read_b128 v[156:159], v164 offset:2048
	ds_read_b128 v[160:163], v164 offset:4096
	ds_read_b128 v[164:167], v164 offset:6144
	v_add_u32_e32 v251, v151, v146
	v_add_u32_e32 v176, s0, v148
	v_add_u32_e32 v186, v176, v147
	ds_read_b128 v[168:171], v186 offset:32768
	ds_read_b128 v[172:175], v186 offset:34816
	ds_read_b128 v[178:181], v186 offset:36864
	ds_read_b128 v[182:185], v186 offset:38912
	v_add_u32_e32 v250, v176, v146
	v_add_u32_e32 v254, s11, v150
	v_add_u32_e32 v228, 0x2000, v254
	v_readfirstlane_b32 s11, v254
	v_lshl_add_u64 v[188:189], v[128:129], 0, s[2:3]
	s_waitcnt lgkmcnt(0)
	v_mfma_f32_16x16x32_bf16 v[124:127], v[152:155], v[168:171], v[124:127]
	ds_read_b128 v[212:215], v186 offset:40960
	v_mfma_f32_16x16x32_bf16 v[120:123], v[152:155], v[172:175], v[120:123]
	ds_read_b128 v[216:219], v186 offset:43008
	v_mfma_f32_16x16x32_bf16 v[116:119], v[152:155], v[178:181], v[116:119]
	ds_read_b128 v[220:223], v186 offset:45056
	v_mfma_f32_16x16x32_bf16 v[112:115], v[152:155], v[182:185], v[112:115]
	ds_read_b128 v[224:227], v186 offset:47104
	v_mfma_f32_16x16x32_bf16 v[104:107], v[156:159], v[168:171], v[104:107]
	ds_read_b128 v[192:195], v251
	v_mfma_f32_16x16x32_bf16 v[96:99], v[156:159], v[172:175], v[96:99]
	ds_read_b128 v[198:201], v251 offset:2048
	v_mfma_f32_16x16x32_bf16 v[88:91], v[156:159], v[178:181], v[88:91]
	ds_read_b128 v[204:207], v251 offset:4096
	v_mfma_f32_16x16x32_bf16 v[80:83], v[156:159], v[182:185], v[80:83]
	ds_read_b128 v[208:211], v251 offset:6144
	v_mfma_f32_16x16x32_bf16 v[72:75], v[160:163], v[168:171], v[72:75]
	s_mov_b32 m0, s11
	v_readfirstlane_b32 s11, v228
	v_mfma_f32_16x16x32_bf16 v[64:67], v[160:163], v[172:175], v[64:67]
	v_add_u32_e32 v228, 0x4000, v254
	global_load_lds_dwordx4 v[188:189], off
	v_mfma_f32_16x16x32_bf16 v[56:59], v[160:163], v[178:181], v[56:59]
	v_lshl_add_u64 v[188:189], v[130:131], 0, s[2:3]
	s_mov_b32 m0, s11
	v_mfma_f32_16x16x32_bf16 v[48:51], v[160:163], v[182:185], v[48:51]
	v_readfirstlane_b32 s11, v228
	v_add_u32_e32 v228, 0x6000, v254
	v_mfma_f32_16x16x32_bf16 v[40:43], v[164:167], v[168:171], v[40:43]
	global_load_lds_dwordx4 v[188:189], off
	v_lshl_add_u64 v[188:189], v[132:133], 0, s[2:3]
	v_mfma_f32_16x16x32_bf16 v[32:35], v[164:167], v[172:175], v[32:35]
	s_mov_b32 m0, s11
	v_readfirstlane_b32 s11, v228
	v_mfma_f32_16x16x32_bf16 v[24:27], v[164:167], v[178:181], v[24:27]
	global_load_lds_dwordx4 v[188:189], off
	v_lshl_add_u64 v[188:189], v[134:135], 0, s[2:3]
	v_mfma_f32_16x16x32_bf16 v[16:19], v[164:167], v[182:185], v[16:19]
	s_mov_b32 m0, s11
	v_add_u32_e32 v253, 0x8000, v254
	s_waitcnt lgkmcnt(4)
	v_mfma_f32_16x16x32_bf16 v[100:103], v[152:155], v[212:215], v[100:103]
	global_load_lds_dwordx4 v[188:189], off
	v_lshl_add_u64 v[188:189], v[136:137], 0, s[2:3]
	v_mfma_f32_16x16x32_bf16 v[92:95], v[152:155], v[216:219], v[92:95]
	s_mov_b64 s[18:19], 0x550080
	v_readfirstlane_b32 s11, v253
	v_mfma_f32_16x16x32_bf16 v[84:87], v[152:155], v[220:223], v[84:87]
	ds_read_b128 v[168:171], v250 offset:32768
	v_add_u32_e32 v253, 0xa000, v254
	v_lshl_add_u64 v[228:229], v[188:189], 0, s[18:19]
	v_mfma_f32_16x16x32_bf16 v[76:79], v[152:155], v[224:227], v[76:79]
	ds_read_b128 v[172:175], v250 offset:34816
	s_mov_b32 m0, s11
	s_mov_b64 s[18:19], 0x572080
	v_mfma_f32_16x16x32_bf16 v[68:71], v[156:159], v[212:215], v[68:71]
	ds_read_b128 v[178:181], v250 offset:36864
	v_readfirstlane_b32 s11, v253
	v_add_u32_e32 v253, 0xc000, v254
	v_mfma_f32_16x16x32_bf16 v[60:63], v[156:159], v[216:219], v[60:63]
	ds_read_b128 v[182:185], v250 offset:38912
	global_load_lds_dwordx4 v[228:229], off
	v_lshl_add_u64 v[228:229], v[188:189], 0, s[18:19]
	v_mfma_f32_16x16x32_bf16 v[52:55], v[156:159], v[220:223], v[52:55]
	s_mov_b32 m0, s11
	s_mov_b64 s[18:19], 0x594080
	v_mfma_f32_16x16x32_bf16 v[44:47], v[156:159], v[224:227], v[44:47]
	v_readfirstlane_b32 s11, v253
	v_add_u32_e32 v254, 0xe000, v254
	v_mfma_f32_16x16x32_bf16 v[36:39], v[160:163], v[212:215], v[36:39]
	global_load_lds_dwordx4 v[228:229], off
	v_lshl_add_u64 v[228:229], v[188:189], 0, s[18:19]
	v_mfma_f32_16x16x32_bf16 v[28:31], v[160:163], v[216:219], v[28:31]
	s_mov_b32 m0, s11
	s_mov_b64 s[18:19], 0x5b6080
	v_mfma_f32_16x16x32_bf16 v[20:23], v[160:163], v[220:223], v[20:23]
	v_readfirstlane_b32 s11, v254
	global_load_lds_dwordx4 v[228:229], off
	v_mfma_f32_16x16x32_bf16 v[12:15], v[160:163], v[224:227], v[12:15]
	v_lshl_add_u64 v[188:189], v[188:189], 0, s[18:19]
	s_mov_b32 m0, s11
	v_mfma_f32_16x16x32_bf16 v[8:11], v[164:167], v[212:215], v[8:11]
	global_load_lds_dwordx4 v[188:189], off
	v_mfma_f32_16x16x32_bf16 v[4:7], v[164:167], v[216:219], v[4:7]
	v_mfma_f32_16x16x32_bf16 v[0:3], v[164:167], v[220:223], v[0:3]
	v_mfma_f32_16x16x32_bf16 v[108:111], v[164:167], v[224:227], v[108:111]
	s_waitcnt lgkmcnt(0)
	v_mfma_f32_16x16x32_bf16 v[124:127], v[192:195], v[168:171], v[124:127]
	ds_read_b128 v[212:215], v250 offset:40960
	v_mfma_f32_16x16x32_bf16 v[120:123], v[192:195], v[172:175], v[120:123]
	ds_read_b128 v[216:219], v250 offset:43008
	v_mfma_f32_16x16x32_bf16 v[116:119], v[192:195], v[178:181], v[116:119]
	ds_read_b128 v[220:223], v250 offset:45056
	v_mfma_f32_16x16x32_bf16 v[112:115], v[192:195], v[182:185], v[112:115]
	ds_read_b128 v[224:227], v250 offset:47104
	v_mfma_f32_16x16x32_bf16 v[104:107], v[198:201], v[168:171], v[104:107]
	v_mfma_f32_16x16x32_bf16 v[96:99], v[198:201], v[172:175], v[96:99]
	v_mfma_f32_16x16x32_bf16 v[88:91], v[198:201], v[178:181], v[88:91]
	v_mfma_f32_16x16x32_bf16 v[80:83], v[198:201], v[182:185], v[80:83]
	v_mfma_f32_16x16x32_bf16 v[72:75], v[204:207], v[168:171], v[72:75]
	v_mfma_f32_16x16x32_bf16 v[64:67], v[204:207], v[172:175], v[64:67]
	v_mfma_f32_16x16x32_bf16 v[56:59], v[204:207], v[178:181], v[56:59]
	v_mfma_f32_16x16x32_bf16 v[48:51], v[204:207], v[182:185], v[48:51]
	v_mfma_f32_16x16x32_bf16 v[40:43], v[208:211], v[168:171], v[40:43]
	v_mfma_f32_16x16x32_bf16 v[32:35], v[208:211], v[172:175], v[32:35]
	v_mfma_f32_16x16x32_bf16 v[24:27], v[208:211], v[178:181], v[24:27]
	v_mfma_f32_16x16x32_bf16 v[16:19], v[208:211], v[182:185], v[16:19]
	s_waitcnt lgkmcnt(0)
	v_mfma_f32_16x16x32_bf16 v[100:103], v[192:195], v[212:215], v[100:103]
	v_mfma_f32_16x16x32_bf16 v[92:95], v[192:195], v[216:219], v[92:95]
	v_mfma_f32_16x16x32_bf16 v[84:87], v[192:195], v[220:223], v[84:87]
	v_mfma_f32_16x16x32_bf16 v[76:79], v[192:195], v[224:227], v[76:79]
	v_mfma_f32_16x16x32_bf16 v[68:71], v[198:201], v[212:215], v[68:71]
	v_mfma_f32_16x16x32_bf16 v[60:63], v[198:201], v[216:219], v[60:63]
	v_mfma_f32_16x16x32_bf16 v[52:55], v[198:201], v[220:223], v[52:55]
	v_mfma_f32_16x16x32_bf16 v[44:47], v[198:201], v[224:227], v[44:47]
	v_mfma_f32_16x16x32_bf16 v[36:39], v[204:207], v[212:215], v[36:39]
	v_mfma_f32_16x16x32_bf16 v[28:31], v[204:207], v[216:219], v[28:31]
	v_mfma_f32_16x16x32_bf16 v[20:23], v[204:207], v[220:223], v[20:23]
	v_mfma_f32_16x16x32_bf16 v[12:15], v[204:207], v[224:227], v[12:15]
	s_add_u32 s2, s2, 0x80
	s_addc_u32 s3, s3, 0
	s_cmpk_eq_i32 s2, 0x780
	s_mov_b32 s0, s1
	v_mfma_f32_16x16x32_bf16 v[8:11], v[208:211], v[212:215], v[8:11]
	v_mfma_f32_16x16x32_bf16 v[4:7], v[208:211], v[216:219], v[4:7]
	v_mfma_f32_16x16x32_bf16 v[0:3], v[208:211], v[220:223], v[0:3]
	v_mfma_f32_16x16x32_bf16 v[108:111], v[208:211], v[224:227], v[108:111]
	s_cbranch_scc0 .LBB0_659
	s_add_i32 s0, 0, 0x10000
	v_add_u32_e32 v136, s0, v149
	v_add_u32_e32 v137, v136, v147
	s_waitcnt vmcnt(0)
	s_barrier
	ds_read_b128 v[128:131], v137
	ds_read_b128 v[132:135], v137 offset:2048
	ds_read_b128 v[150:153], v137 offset:4096
	ds_read_b128 v[154:157], v137 offset:6144
	v_add_u32_e32 v137, s0, v148
	v_add_u32_e32 v147, v137, v147
	ds_read_b128 v[158:161], v147 offset:32768
	ds_read_b128 v[162:165], v147 offset:34816
	ds_read_b128 v[166:169], v147 offset:36864
	ds_read_b128 v[170:173], v147 offset:38912
	s_waitcnt lgkmcnt(0)
	v_mfma_f32_16x16x32_bf16 v[124:127], v[128:131], v[158:161], v[124:127]
	v_mfma_f32_16x16x32_bf16 v[120:123], v[128:131], v[162:165], v[120:123]
	v_mfma_f32_16x16x32_bf16 v[116:119], v[128:131], v[166:169], v[116:119]
	v_mfma_f32_16x16x32_bf16 v[112:115], v[128:131], v[170:173], v[112:115]
	v_mfma_f32_16x16x32_bf16 v[104:107], v[132:135], v[158:161], v[104:107]
	v_mfma_f32_16x16x32_bf16 v[72:75], v[150:153], v[158:161], v[72:75]
	v_mfma_f32_16x16x32_bf16 v[64:67], v[150:153], v[162:165], v[64:67]
	v_mfma_f32_16x16x32_bf16 v[56:59], v[150:153], v[166:169], v[56:59]
	v_mfma_f32_16x16x32_bf16 v[48:51], v[150:153], v[170:173], v[48:51]
	v_mfma_f32_16x16x32_bf16 v[178:181], v[132:135], v[162:165], v[96:99]
	v_mfma_f32_16x16x32_bf16 v[182:185], v[132:135], v[166:169], v[88:91]
	v_mfma_f32_16x16x32_bf16 v[186:189], v[132:135], v[170:173], v[80:83]
	v_mfma_f32_16x16x32_bf16 v[158:161], v[154:157], v[158:161], v[40:43]
	v_mfma_f32_16x16x32_bf16 v[162:165], v[154:157], v[162:165], v[32:35]
	v_mfma_f32_16x16x32_bf16 v[166:169], v[154:157], v[166:169], v[24:27]
	v_mfma_f32_16x16x32_bf16 v[170:173], v[154:157], v[170:173], v[16:19]
	s_nop 2
	ds_read_b128 v[16:19], v147 offset:40960
	ds_read_b128 v[24:27], v147 offset:43008
	ds_read_b128 v[32:35], v147 offset:45056
	ds_read_b128 v[40:43], v147 offset:47104
	s_waitcnt lgkmcnt(0)
	v_mfma_f32_16x16x32_bf16 v[100:103], v[128:131], v[16:19], v[100:103]
	v_mfma_f32_16x16x32_bf16 v[92:95], v[128:131], v[24:27], v[92:95]
	v_mfma_f32_16x16x32_bf16 v[192:195], v[128:131], v[32:35], v[84:87]
	v_mfma_f32_16x16x32_bf16 v[76:79], v[128:131], v[40:43], v[76:79]
	v_mfma_f32_16x16x32_bf16 v[68:71], v[132:135], v[16:19], v[68:71]
	v_mfma_f32_16x16x32_bf16 v[60:63], v[132:135], v[24:27], v[60:63]
	v_mfma_f32_16x16x32_bf16 v[128:131], v[132:135], v[32:35], v[52:55]
	v_mfma_f32_16x16x32_bf16 v[44:47], v[132:135], v[40:43], v[44:47]
	v_mfma_f32_16x16x32_bf16 v[132:135], v[150:153], v[16:19], v[36:39]
	v_mfma_f32_16x16x32_bf16 v[198:201], v[150:153], v[24:27], v[28:31]
	v_mfma_f32_16x16x32_bf16 v[204:207], v[150:153], v[32:35], v[20:23]
	v_mfma_f32_16x16x32_bf16 v[148:151], v[150:153], v[40:43], v[12:15]
	v_mfma_f32_16x16x32_bf16 v[208:211], v[154:157], v[16:19], v[8:11]
	v_mfma_f32_16x16x32_bf16 v[212:215], v[154:157], v[24:27], v[4:7]
	v_mfma_f32_16x16x32_bf16 v[216:219], v[154:157], v[32:35], v[0:3]
	v_mfma_f32_16x16x32_bf16 v[154:157], v[154:157], v[40:43], v[108:111]
	s_nop 1
	v_add_u32_e32 v0, v136, v146
	v_add_u32_e32 v136, v137, v146
	ds_read_b128 v[108:111], v0
	ds_read_b128 v[220:223], v0 offset:2048
	ds_read_b128 v[224:227], v0 offset:4096
	ds_read_b128 v[228:231], v0 offset:6144
	ds_read_b128 v[0:3], v136 offset:32768
	ds_read_b128 v[4:7], v136 offset:34816
	ds_read_b128 v[232:235], v136 offset:36864
	ds_read_b128 v[236:239], v136 offset:38912
	s_waitcnt lgkmcnt(0)
	v_mfma_f32_16x16x32_bf16 v[88:91], v[108:111], v[0:3], v[124:127]
	v_mfma_f32_16x16x32_bf16 v[96:99], v[108:111], v[4:7], v[120:123]
	v_mfma_f32_16x16x32_bf16 v[80:83], v[108:111], v[232:235], v[116:119]
	v_mfma_f32_16x16x32_bf16 v[84:87], v[108:111], v[236:239], v[112:115]
	v_mfma_f32_16x16x32_bf16 v[40:43], v[220:223], v[0:3], v[104:107]
	v_mfma_f32_16x16x32_bf16 v[52:55], v[220:223], v[4:7], v[178:181]
	v_mfma_f32_16x16x32_bf16 v[32:35], v[220:223], v[232:235], v[182:185]
	v_mfma_f32_16x16x32_bf16 v[36:39], v[220:223], v[236:239], v[186:189]
	v_mfma_f32_16x16x32_bf16 v[24:27], v[224:227], v[0:3], v[72:75]
	v_mfma_f32_16x16x32_bf16 v[28:31], v[224:227], v[4:7], v[64:67]
	v_mfma_f32_16x16x32_bf16 v[16:19], v[224:227], v[232:235], v[56:59]
	v_mfma_f32_16x16x32_bf16 v[20:23], v[224:227], v[236:239], v[48:51]
	v_mfma_f32_16x16x32_bf16 v[8:11], v[228:231], v[0:3], v[158:161]
	v_mfma_f32_16x16x32_bf16 v[12:15], v[228:231], v[4:7], v[162:165]
	v_mfma_f32_16x16x32_bf16 v[0:3], v[228:231], v[232:235], v[166:169]
	v_mfma_f32_16x16x32_bf16 v[4:7], v[228:231], v[236:239], v[170:173]
	ds_read_b128 v[48:51], v136 offset:40960
	ds_read_b128 v[64:67], v136 offset:43008
	ds_read_b128 v[158:161], v136 offset:45056
	ds_read_b128 v[162:165], v136 offset:47104
	s_waitcnt lgkmcnt(0)
	v_mfma_f32_16x16x32_bf16 v[104:107], v[220:223], v[48:51], v[68:71]
	v_cmp_ne_u32_e32 vcc, 0, v138
	v_cmp_eq_u32_e64 s[2:3], 0, v138
	s_waitcnt vmcnt(0)
	v_lshl_or_b32 v68, v140, 2, v141
	v_lshl_add_u32 v69, v139, 2, 0
	v_mfma_f32_16x16x32_bf16 v[120:123], v[108:111], v[48:51], v[100:103]
	v_lshl_add_u32 v152, v68, 9, v69
	v_add_u32_e32 v153, 0x400, v152
	v_add_u32_e32 v147, 0x6000, v152
	v_mfma_f32_16x16x32_bf16 v[124:127], v[108:111], v[64:67], v[92:95]
	v_add_u32_e32 v146, 0x6400, v152
	s_barrier
	v_mfma_f32_16x16x32_bf16 v[112:115], v[108:111], v[158:161], v[192:195]
	v_mfma_f32_16x16x32_bf16 v[116:119], v[108:111], v[162:165], v[76:79]
	v_mfma_f32_16x16x32_bf16 v[108:111], v[220:223], v[64:67], v[60:63]
	v_mfma_f32_16x16x32_bf16 v[92:95], v[220:223], v[158:161], v[128:131]
	v_mfma_f32_16x16x32_bf16 v[100:103], v[220:223], v[162:165], v[44:47]
	v_mfma_f32_16x16x32_bf16 v[56:59], v[224:227], v[48:51], v[132:135]
	v_mfma_f32_16x16x32_bf16 v[60:63], v[224:227], v[64:67], v[198:201]
	v_mfma_f32_16x16x32_bf16 v[44:47], v[224:227], v[158:161], v[204:207]
	v_mfma_f32_16x16x32_bf16 v[72:75], v[224:227], v[162:165], v[148:151]
	v_mfma_f32_16x16x32_bf16 v[48:51], v[228:231], v[48:51], v[208:211]
	s_nop 1
	v_add_u32_e32 v151, 0x2000, v152
	v_add_u32_e32 v150, 0x2400, v152
	v_add_u32_e32 v149, 0x4000, v152
	v_mfma_f32_16x16x32_bf16 v[64:67], v[228:231], v[64:67], v[212:215]
	v_add_u32_e32 v148, 0x4400, v152
	v_mfma_f32_16x16x32_bf16 v[68:71], v[228:231], v[158:161], v[216:219]
	v_mfma_f32_16x16x32_bf16 v[76:79], v[228:231], v[162:165], v[154:157]
	s_and_saveexec_b64 s[0:1], s[2:3]
	s_cbranch_execz .LBB0_662
	ds_write2_b32 v152, v88, v96 offset1:16
	ds_write2_b32 v152, v89, v97 offset0:128 offset1:144
	ds_write2_b32 v153, v90, v98 offset1:16
	ds_write2_b32 v153, v91, v99 offset0:128 offset1:144
	ds_write2_b32 v152, v80, v84 offset0:32 offset1:48
	ds_write2_b32 v152, v81, v85 offset0:160 offset1:176
	ds_write2_b32 v153, v82, v86 offset0:32 offset1:48
	ds_write2_b32 v153, v83, v87 offset0:160 offset1:176
	ds_write2_b32 v152, v120, v124 offset0:64 offset1:80
	ds_write2_b32 v152, v121, v125 offset0:192 offset1:208
	ds_write2_b32 v153, v122, v126 offset0:64 offset1:80
	ds_write2_b32 v153, v123, v127 offset0:192 offset1:208
	ds_write2_b32 v152, v112, v116 offset0:96 offset1:112
	ds_write2_b32 v152, v113, v117 offset0:224 offset1:240
	ds_write2_b32 v153, v114, v118 offset0:96 offset1:112
	ds_write2_b32 v153, v115, v119 offset0:224 offset1:240
	ds_write2_b32 v151, v40, v52 offset1:16
	ds_write2_b32 v151, v41, v53 offset0:128 offset1:144
	ds_write2_b32 v150, v42, v54 offset1:16
	ds_write2_b32 v150, v43, v55 offset0:128 offset1:144
	ds_write2_b32 v151, v32, v36 offset0:32 offset1:48
	ds_write2_b32 v151, v33, v37 offset0:160 offset1:176
	ds_write2_b32 v150, v34, v38 offset0:32 offset1:48
	ds_write2_b32 v150, v35, v39 offset0:160 offset1:176
	ds_write2_b32 v151, v104, v108 offset0:64 offset1:80
	ds_write2_b32 v151, v105, v109 offset0:192 offset1:208
	ds_write2_b32 v150, v106, v110 offset0:64 offset1:80
	ds_write2_b32 v150, v107, v111 offset0:192 offset1:208
	ds_write2_b32 v151, v92, v100 offset0:96 offset1:112
	ds_write2_b32 v151, v93, v101 offset0:224 offset1:240
	ds_write2_b32 v150, v94, v102 offset0:96 offset1:112
	ds_write2_b32 v150, v95, v103 offset0:224 offset1:240
	ds_write2_b32 v149, v24, v28 offset1:16
	ds_write2_b32 v149, v25, v29 offset0:128 offset1:144
	ds_write2_b32 v148, v26, v30 offset1:16
	ds_write2_b32 v148, v27, v31 offset0:128 offset1:144
	ds_write2_b32 v149, v16, v20 offset0:32 offset1:48
	ds_write2_b32 v149, v17, v21 offset0:160 offset1:176
	ds_write2_b32 v148, v18, v22 offset0:32 offset1:48
	ds_write2_b32 v148, v19, v23 offset0:160 offset1:176
	ds_write2_b32 v149, v56, v60 offset0:64 offset1:80
	ds_write2_b32 v149, v57, v61 offset0:192 offset1:208
	ds_write2_b32 v148, v58, v62 offset0:64 offset1:80
	ds_write2_b32 v148, v59, v63 offset0:192 offset1:208
	ds_write2_b32 v149, v44, v72 offset0:96 offset1:112
	ds_write2_b32 v149, v45, v73 offset0:224 offset1:240
	ds_write2_b32 v148, v46, v74 offset0:96 offset1:112
	ds_write2_b32 v148, v47, v75 offset0:224 offset1:240
	ds_write2_b32 v147, v8, v12 offset1:16
	ds_write2_b32 v147, v9, v13 offset0:128 offset1:144
	ds_write2_b32 v146, v10, v14 offset1:16
	ds_write2_b32 v146, v11, v15 offset0:128 offset1:144
	ds_write2_b32 v147, v0, v4 offset0:32 offset1:48
	ds_write2_b32 v147, v1, v5 offset0:160 offset1:176
	ds_write2_b32 v146, v2, v6 offset0:32 offset1:48
	ds_write2_b32 v146, v3, v7 offset0:160 offset1:176
	ds_write2_b32 v147, v48, v64 offset0:64 offset1:80
	ds_write2_b32 v147, v49, v65 offset0:192 offset1:208
	ds_write2_b32 v146, v50, v66 offset0:64 offset1:80
	ds_write2_b32 v146, v51, v67 offset0:192 offset1:208
	ds_write2_b32 v147, v68, v76 offset0:96 offset1:112
	ds_write2_b32 v147, v69, v77 offset0:224 offset1:240
	ds_write2_b32 v146, v70, v78 offset0:96 offset1:112
	ds_write2_b32 v146, v71, v79 offset0:224 offset1:240

.LBB0_1074:
	s_add_i32 s5, s4, 0x10000
	s_and_b32 s40, s5, 0x10000
	s_waitcnt vmcnt(0)
	s_barrier
	s_and_b32 s4, s4, 0x10000
	s_add_i32 s4, s4, 0
	v_add_u32_e32 v147, s4, v144
	v_add_u32_e32 v160, v147, v143
	ds_read_b128 v[148:151], v160
	ds_read_b128 v[152:155], v160 offset:2048
	ds_read_b128 v[156:159], v160 offset:4096
	ds_read_b128 v[170:173], v160 offset:6144
	v_add_u32_e32 v251, v147, v142
	v_add_u32_e32 v160, s4, v145
	v_add_u32_e32 v161, v160, v143
	ds_read_b128 v[178:181], v161 offset:32768
	ds_read_b128 v[182:185], v161 offset:34816
	ds_read_b128 v[186:189], v161 offset:36864
	ds_read_b128 v[192:195], v161 offset:38912
	v_add_u32_e32 v250, v160, v142
	v_add_u32_e32 v254, s40, v146
	v_add_u32_e32 v232, 0x2000, v254
	v_readfirstlane_b32 s40, v254
	v_lshl_add_u64 v[174:175], v[136:137], 0, s[2:3]
	s_waitcnt lgkmcnt(0)
	v_mfma_f32_16x16x32_bf16 v[124:127], v[148:151], v[178:181], v[124:127]
	ds_read_b128 v[216:219], v161 offset:40960
	v_mfma_f32_16x16x32_bf16 v[120:123], v[148:151], v[182:185], v[120:123]
	ds_read_b128 v[220:223], v161 offset:43008
	v_mfma_f32_16x16x32_bf16 v[116:119], v[148:151], v[186:189], v[116:119]
	ds_read_b128 v[224:227], v161 offset:45056
	v_mfma_f32_16x16x32_bf16 v[112:115], v[148:151], v[192:195], v[112:115]
	ds_read_b128 v[228:231], v161 offset:47104
	v_mfma_f32_16x16x32_bf16 v[104:107], v[152:155], v[178:181], v[104:107]
	ds_read_b128 v[198:201], v251
	v_mfma_f32_16x16x32_bf16 v[96:99], v[152:155], v[182:185], v[96:99]
	ds_read_b128 v[204:207], v251 offset:2048
	v_mfma_f32_16x16x32_bf16 v[88:91], v[152:155], v[186:189], v[88:91]
	ds_read_b128 v[208:211], v251 offset:4096
	v_mfma_f32_16x16x32_bf16 v[80:83], v[152:155], v[192:195], v[80:83]
	ds_read_b128 v[212:215], v251 offset:6144
	v_mfma_f32_16x16x32_bf16 v[72:75], v[156:159], v[178:181], v[72:75]
	s_mov_b32 m0, s40
	v_readfirstlane_b32 s40, v232
	v_mfma_f32_16x16x32_bf16 v[64:67], v[156:159], v[182:185], v[64:67]
	v_add_u32_e32 v232, 0x4000, v254
	global_load_lds_dwordx4 v[174:175], off
	v_mfma_f32_16x16x32_bf16 v[56:59], v[156:159], v[186:189], v[56:59]
	v_lshl_add_u64 v[174:175], v[134:135], 0, s[2:3]
	s_mov_b32 m0, s40
	v_mfma_f32_16x16x32_bf16 v[48:51], v[156:159], v[192:195], v[48:51]
	v_readfirstlane_b32 s40, v232
	v_add_u32_e32 v232, 0x6000, v254
	v_mfma_f32_16x16x32_bf16 v[40:43], v[170:173], v[178:181], v[40:43]
	global_load_lds_dwordx4 v[174:175], off
	v_lshl_add_u64 v[174:175], v[132:133], 0, s[2:3]
	v_mfma_f32_16x16x32_bf16 v[32:35], v[170:173], v[182:185], v[32:35]
	s_mov_b32 m0, s40
	v_readfirstlane_b32 s40, v232
	v_mfma_f32_16x16x32_bf16 v[24:27], v[170:173], v[186:189], v[24:27]
	global_load_lds_dwordx4 v[174:175], off
	v_lshl_add_u64 v[174:175], v[130:131], 0, s[2:3]
	v_mfma_f32_16x16x32_bf16 v[16:19], v[170:173], v[192:195], v[16:19]
	s_mov_b32 m0, s40
	s_mov_b64 s[40:41], 0x770080
	s_waitcnt lgkmcnt(4)
	v_mfma_f32_16x16x32_bf16 v[100:103], v[148:151], v[216:219], v[100:103]
	global_load_lds_dwordx4 v[174:175], off
	v_lshl_add_u64 v[174:175], v[128:129], 0, s[2:3]
	v_mfma_f32_16x16x32_bf16 v[92:95], v[148:151], v[220:223], v[92:95]
	v_add_u32_e32 v253, 0x8000, v254
	v_lshl_add_u64 v[232:233], v[174:175], 0, s[40:41]
	v_mfma_f32_16x16x32_bf16 v[84:87], v[148:151], v[224:227], v[84:87]
	ds_read_b128 v[178:181], v250 offset:32768
	v_readfirstlane_b32 s40, v253
	s_mov_b32 m0, s40
	v_mfma_f32_16x16x32_bf16 v[76:79], v[148:151], v[228:231], v[76:79]
	ds_read_b128 v[182:185], v250 offset:34816
	s_mov_b64 s[40:41], 0x792080
	v_add_u32_e32 v253, 0xa000, v254
	v_mfma_f32_16x16x32_bf16 v[68:71], v[152:155], v[216:219], v[68:71]
	ds_read_b128 v[186:189], v250 offset:36864
	global_load_lds_dwordx4 v[232:233], off
	v_lshl_add_u64 v[232:233], v[174:175], 0, s[40:41]
	v_mfma_f32_16x16x32_bf16 v[60:63], v[152:155], v[220:223], v[60:63]
	ds_read_b128 v[192:195], v250 offset:38912
	v_readfirstlane_b32 s40, v253
	s_mov_b32 m0, s40
	v_mfma_f32_16x16x32_bf16 v[52:55], v[152:155], v[224:227], v[52:55]
	s_mov_b64 s[40:41], 0x7b4080
	v_add_u32_e32 v253, 0xc000, v254
	v_mfma_f32_16x16x32_bf16 v[44:47], v[152:155], v[228:231], v[44:47]
	global_load_lds_dwordx4 v[232:233], off
	v_lshl_add_u64 v[232:233], v[174:175], 0, s[40:41]
	v_mfma_f32_16x16x32_bf16 v[36:39], v[156:159], v[216:219], v[36:39]
	v_readfirstlane_b32 s40, v253
	s_mov_b32 m0, s40
	v_mfma_f32_16x16x32_bf16 v[28:31], v[156:159], v[220:223], v[28:31]
	s_mov_b64 s[40:41], 0x7d6080
	v_add_u32_e32 v254, 0xe000, v254
	v_mfma_f32_16x16x32_bf16 v[20:23], v[156:159], v[224:227], v[20:23]
	v_lshl_add_u64 v[174:175], v[174:175], 0, s[40:41]
	v_readfirstlane_b32 s40, v254
	v_mfma_f32_16x16x32_bf16 v[12:15], v[156:159], v[228:231], v[12:15]
	global_load_lds_dwordx4 v[232:233], off
	s_mov_b32 m0, s40
	v_mfma_f32_16x16x32_bf16 v[8:11], v[170:173], v[216:219], v[8:11]
	global_load_lds_dwordx4 v[174:175], off
	v_mfma_f32_16x16x32_bf16 v[4:7], v[170:173], v[220:223], v[4:7]
	v_mfma_f32_16x16x32_bf16 v[0:3], v[170:173], v[224:227], v[0:3]
	v_mfma_f32_16x16x32_bf16 v[108:111], v[170:173], v[228:231], v[108:111]
	s_waitcnt lgkmcnt(0)
	v_mfma_f32_16x16x32_bf16 v[124:127], v[198:201], v[178:181], v[124:127]
	ds_read_b128 v[216:219], v250 offset:40960
	v_mfma_f32_16x16x32_bf16 v[120:123], v[198:201], v[182:185], v[120:123]
	ds_read_b128 v[220:223], v250 offset:43008
	v_mfma_f32_16x16x32_bf16 v[116:119], v[198:201], v[186:189], v[116:119]
	ds_read_b128 v[224:227], v250 offset:45056
	v_mfma_f32_16x16x32_bf16 v[112:115], v[198:201], v[192:195], v[112:115]
	ds_read_b128 v[228:231], v250 offset:47104
	v_mfma_f32_16x16x32_bf16 v[104:107], v[204:207], v[178:181], v[104:107]
	v_mfma_f32_16x16x32_bf16 v[96:99], v[204:207], v[182:185], v[96:99]
	v_mfma_f32_16x16x32_bf16 v[88:91], v[204:207], v[186:189], v[88:91]
	v_mfma_f32_16x16x32_bf16 v[80:83], v[204:207], v[192:195], v[80:83]
	v_mfma_f32_16x16x32_bf16 v[72:75], v[208:211], v[178:181], v[72:75]
	v_mfma_f32_16x16x32_bf16 v[64:67], v[208:211], v[182:185], v[64:67]
	v_mfma_f32_16x16x32_bf16 v[56:59], v[208:211], v[186:189], v[56:59]
	v_mfma_f32_16x16x32_bf16 v[48:51], v[208:211], v[192:195], v[48:51]
	v_mfma_f32_16x16x32_bf16 v[40:43], v[212:215], v[178:181], v[40:43]
	v_mfma_f32_16x16x32_bf16 v[32:35], v[212:215], v[182:185], v[32:35]
	v_mfma_f32_16x16x32_bf16 v[24:27], v[212:215], v[186:189], v[24:27]
	v_mfma_f32_16x16x32_bf16 v[16:19], v[212:215], v[192:195], v[16:19]
	s_waitcnt lgkmcnt(0)
	v_mfma_f32_16x16x32_bf16 v[100:103], v[198:201], v[216:219], v[100:103]
	v_mfma_f32_16x16x32_bf16 v[92:95], v[198:201], v[220:223], v[92:95]
	v_mfma_f32_16x16x32_bf16 v[84:87], v[198:201], v[224:227], v[84:87]
	v_mfma_f32_16x16x32_bf16 v[76:79], v[198:201], v[228:231], v[76:79]
	v_mfma_f32_16x16x32_bf16 v[68:71], v[204:207], v[216:219], v[68:71]
	v_mfma_f32_16x16x32_bf16 v[60:63], v[204:207], v[220:223], v[60:63]
	v_mfma_f32_16x16x32_bf16 v[52:55], v[204:207], v[224:227], v[52:55]
	v_mfma_f32_16x16x32_bf16 v[44:47], v[204:207], v[228:231], v[44:47]
	v_mfma_f32_16x16x32_bf16 v[36:39], v[208:211], v[216:219], v[36:39]
	v_mfma_f32_16x16x32_bf16 v[28:31], v[208:211], v[220:223], v[28:31]
	v_mfma_f32_16x16x32_bf16 v[20:23], v[208:211], v[224:227], v[20:23]
	v_mfma_f32_16x16x32_bf16 v[12:15], v[208:211], v[228:231], v[12:15]
	s_add_u32 s2, s2, 0x80
	s_addc_u32 s3, s3, 0
	s_cmpk_eq_i32 s2, 0x780
	s_mov_b32 s4, s5
	v_mfma_f32_16x16x32_bf16 v[8:11], v[212:215], v[216:219], v[8:11]
	v_mfma_f32_16x16x32_bf16 v[4:7], v[212:215], v[220:223], v[4:7]
	v_mfma_f32_16x16x32_bf16 v[0:3], v[212:215], v[224:227], v[0:3]
	v_mfma_f32_16x16x32_bf16 v[108:111], v[212:215], v[228:231], v[108:111]
	s_cbranch_scc0 .LBB0_1074
	s_add_i32 s2, 0, 0x10000
	v_add_u32_e32 v136, s2, v145
	v_add_u32_e32 v174, s2, v144
	v_add_u32_e32 v137, v136, v143
	v_add_u32_e32 v143, v174, v143
	s_waitcnt vmcnt(0)
	s_barrier
	ds_read_b128 v[128:131], v137 offset:38912
	ds_read_b128 v[132:135], v137 offset:36864
	ds_read_b128 v[146:149], v137 offset:34816
	ds_read_b128 v[150:153], v137 offset:32768
	ds_read_b128 v[154:157], v143 offset:6144
	ds_read_b128 v[158:161], v143 offset:4096
	ds_read_b128 v[170:173], v143 offset:2048
	ds_read_b128 v[178:181], v143
	s_waitcnt lgkmcnt(0)
	v_mfma_f32_16x16x32_bf16 v[124:127], v[178:181], v[150:153], v[124:127]
	v_mfma_f32_16x16x32_bf16 v[120:123], v[178:181], v[146:149], v[120:123]
	v_mfma_f32_16x16x32_bf16 v[116:119], v[178:181], v[132:135], v[116:119]
	v_mfma_f32_16x16x32_bf16 v[112:115], v[178:181], v[128:131], v[112:115]
	v_mfma_f32_16x16x32_bf16 v[104:107], v[170:173], v[150:153], v[104:107]
	v_mfma_f32_16x16x32_bf16 v[72:75], v[158:161], v[150:153], v[72:75]
	v_mfma_f32_16x16x32_bf16 v[64:67], v[158:161], v[146:149], v[64:67]
	v_mfma_f32_16x16x32_bf16 v[56:59], v[158:161], v[132:135], v[56:59]
	v_mfma_f32_16x16x32_bf16 v[48:51], v[158:161], v[128:131], v[48:51]
	v_mfma_f32_16x16x32_bf16 v[182:185], v[170:173], v[146:149], v[96:99]
	v_mfma_f32_16x16x32_bf16 v[186:189], v[170:173], v[132:135], v[88:91]
	v_mfma_f32_16x16x32_bf16 v[192:195], v[170:173], v[128:131], v[80:83]
	v_mfma_f32_16x16x32_bf16 v[150:153], v[154:157], v[150:153], v[40:43]
	v_mfma_f32_16x16x32_bf16 v[144:147], v[154:157], v[146:149], v[32:35]
	v_mfma_f32_16x16x32_bf16 v[132:135], v[154:157], v[132:135], v[24:27]
	v_mfma_f32_16x16x32_bf16 v[128:131], v[154:157], v[128:131], v[16:19]
	s_nop 2
	ds_read_b128 v[16:19], v137 offset:40960
	ds_read_b128 v[24:27], v137 offset:43008
	ds_read_b128 v[32:35], v137 offset:45056
	ds_read_b128 v[40:43], v137 offset:47104
	s_waitcnt lgkmcnt(0)
	v_mfma_f32_16x16x32_bf16 v[100:103], v[178:181], v[16:19], v[100:103]
	v_mfma_f32_16x16x32_bf16 v[92:95], v[178:181], v[24:27], v[92:95]
	v_mfma_f32_16x16x32_bf16 v[198:201], v[178:181], v[32:35], v[84:87]
	v_mfma_f32_16x16x32_bf16 v[76:79], v[178:181], v[40:43], v[76:79]
	v_mfma_f32_16x16x32_bf16 v[68:71], v[170:173], v[16:19], v[68:71]
	v_mfma_f32_16x16x32_bf16 v[60:63], v[170:173], v[24:27], v[60:63]
	v_mfma_f32_16x16x32_bf16 v[178:181], v[170:173], v[32:35], v[52:55]
	v_mfma_f32_16x16x32_bf16 v[44:47], v[170:173], v[40:43], v[44:47]
	v_mfma_f32_16x16x32_bf16 v[170:173], v[158:161], v[16:19], v[36:39]
	v_mfma_f32_16x16x32_bf16 v[204:207], v[158:161], v[24:27], v[28:31]
	v_mfma_f32_16x16x32_bf16 v[208:211], v[158:161], v[32:35], v[20:23]
	v_mfma_f32_16x16x32_bf16 v[158:161], v[158:161], v[40:43], v[12:15]
	v_mfma_f32_16x16x32_bf16 v[212:215], v[154:157], v[16:19], v[8:11]
	v_mfma_f32_16x16x32_bf16 v[216:219], v[154:157], v[24:27], v[4:7]
	v_mfma_f32_16x16x32_bf16 v[220:223], v[154:157], v[32:35], v[0:3]
	v_mfma_f32_16x16x32_bf16 v[154:157], v[154:157], v[40:43], v[108:111]
	s_nop 1
	v_add_u32_e32 v0, v174, v142
	v_add_u32_e32 v136, v136, v142
	ds_read_b128 v[108:111], v0
	ds_read_b128 v[224:227], v0 offset:2048
	ds_read_b128 v[228:231], v0 offset:4096
	ds_read_b128 v[232:235], v0 offset:6144
	ds_read_b128 v[0:3], v136 offset:32768
	ds_read_b128 v[4:7], v136 offset:34816
	ds_read_b128 v[236:239], v136 offset:36864
	ds_read_b128 v[240:243], v136 offset:38912
	s_waitcnt lgkmcnt(0)
	v_mfma_f32_16x16x32_bf16 v[88:91], v[108:111], v[0:3], v[124:127]
	v_mfma_f32_16x16x32_bf16 v[96:99], v[108:111], v[4:7], v[120:123]
	v_mfma_f32_16x16x32_bf16 v[80:83], v[108:111], v[236:239], v[116:119]
	v_mfma_f32_16x16x32_bf16 v[84:87], v[108:111], v[240:243], v[112:115]
	v_mfma_f32_16x16x32_bf16 v[40:43], v[224:227], v[0:3], v[104:107]
	v_mfma_f32_16x16x32_bf16 v[52:55], v[224:227], v[4:7], v[182:185]
	v_mfma_f32_16x16x32_bf16 v[32:35], v[224:227], v[236:239], v[186:189]
	v_mfma_f32_16x16x32_bf16 v[36:39], v[224:227], v[240:243], v[192:195]
	v_mfma_f32_16x16x32_bf16 v[24:27], v[228:231], v[0:3], v[72:75]
	v_mfma_f32_16x16x32_bf16 v[28:31], v[228:231], v[4:7], v[64:67]
	v_mfma_f32_16x16x32_bf16 v[16:19], v[228:231], v[236:239], v[56:59]
	v_mfma_f32_16x16x32_bf16 v[20:23], v[228:231], v[240:243], v[48:51]
	v_mfma_f32_16x16x32_bf16 v[8:11], v[232:235], v[0:3], v[150:153]
	v_mfma_f32_16x16x32_bf16 v[12:15], v[232:235], v[4:7], v[144:147]
	v_mfma_f32_16x16x32_bf16 v[0:3], v[232:235], v[236:239], v[132:135]
	v_mfma_f32_16x16x32_bf16 v[4:7], v[232:235], v[240:243], v[128:131]
	ds_read_b128 v[48:51], v136 offset:40960
	ds_read_b128 v[64:67], v136 offset:43008
	s_nop 0
	ds_read_b128 v[128:131], v136 offset:45056
	ds_read_b128 v[132:135], v136 offset:47104
	s_waitcnt lgkmcnt(0)
	v_mfma_f32_16x16x32_bf16 v[104:107], v[224:227], v[48:51], v[68:71]
	v_cmp_ne_u32_e32 vcc, 0, v138
	v_cmp_eq_u32_e64 s[2:3], 0, v138
	s_waitcnt vmcnt(0)
	v_lshl_or_b32 v68, v140, 2, v141
	v_lshl_add_u32 v69, v139, 2, 0
	v_mfma_f32_16x16x32_bf16 v[120:123], v[108:111], v[48:51], v[100:103]
	s_barrier
	v_mfma_f32_16x16x32_bf16 v[124:127], v[108:111], v[64:67], v[92:95]
	v_mfma_f32_16x16x32_bf16 v[112:115], v[108:111], v[128:131], v[198:201]
	v_mfma_f32_16x16x32_bf16 v[116:119], v[108:111], v[132:135], v[76:79]
	v_mfma_f32_16x16x32_bf16 v[108:111], v[224:227], v[64:67], v[60:63]
	v_mfma_f32_16x16x32_bf16 v[92:95], v[224:227], v[128:131], v[178:181]
	v_mfma_f32_16x16x32_bf16 v[100:103], v[224:227], v[132:135], v[44:47]
	s_nop 1
	v_lshl_add_u32 v178, v68, 9, v69
	v_add_u32_e32 v179, 0x400, v178
	v_add_u32_e32 v176, 0x2000, v178
	v_mfma_f32_16x16x32_bf16 v[56:59], v[228:231], v[48:51], v[170:173]
	v_add_u32_e32 v175, 0x2400, v178
	v_add_u32_e32 v174, 0x4000, v178
	v_mfma_f32_16x16x32_bf16 v[60:63], v[228:231], v[64:67], v[204:207]
	v_add_u32_e32 v173, 0x4400, v178
	v_add_u32_e32 v172, 0x6000, v178
	v_add_u32_e32 v171, 0x6400, v178
	v_mfma_f32_16x16x32_bf16 v[44:47], v[228:231], v[128:131], v[208:211]
	v_mfma_f32_16x16x32_bf16 v[72:75], v[228:231], v[132:135], v[158:161]
	v_mfma_f32_16x16x32_bf16 v[48:51], v[232:235], v[48:51], v[212:215]
	v_mfma_f32_16x16x32_bf16 v[64:67], v[232:235], v[64:67], v[216:219]
	v_mfma_f32_16x16x32_bf16 v[68:71], v[232:235], v[128:131], v[220:223]
	v_mfma_f32_16x16x32_bf16 v[76:79], v[232:235], v[132:135], v[154:157]
	s_and_saveexec_b64 s[4:5], s[2:3]
	s_cbranch_execz .LBB0_1077
	ds_write2_b32 v178, v88, v96 offset1:16
	ds_write2_b32 v178, v89, v97 offset0:128 offset1:144
	ds_write2_b32 v179, v90, v98 offset1:16
	ds_write2_b32 v179, v91, v99 offset0:128 offset1:144
	ds_write2_b32 v178, v80, v84 offset0:32 offset1:48
	ds_write2_b32 v178, v81, v85 offset0:160 offset1:176
	ds_write2_b32 v179, v82, v86 offset0:32 offset1:48
	ds_write2_b32 v179, v83, v87 offset0:160 offset1:176
	ds_write2_b32 v178, v120, v124 offset0:64 offset1:80
	ds_write2_b32 v178, v121, v125 offset0:192 offset1:208
	ds_write2_b32 v179, v122, v126 offset0:64 offset1:80
	ds_write2_b32 v179, v123, v127 offset0:192 offset1:208
	ds_write2_b32 v178, v112, v116 offset0:96 offset1:112
	ds_write2_b32 v178, v113, v117 offset0:224 offset1:240
	ds_write2_b32 v179, v114, v118 offset0:96 offset1:112
	ds_write2_b32 v179, v115, v119 offset0:224 offset1:240
	ds_write2_b32 v176, v40, v52 offset1:16
	ds_write2_b32 v176, v41, v53 offset0:128 offset1:144
	ds_write2_b32 v175, v42, v54 offset1:16
	ds_write2_b32 v175, v43, v55 offset0:128 offset1:144
	ds_write2_b32 v176, v32, v36 offset0:32 offset1:48
	ds_write2_b32 v176, v33, v37 offset0:160 offset1:176
	ds_write2_b32 v175, v34, v38 offset0:32 offset1:48
	ds_write2_b32 v175, v35, v39 offset0:160 offset1:176
	ds_write2_b32 v176, v104, v108 offset0:64 offset1:80
	ds_write2_b32 v176, v105, v109 offset0:192 offset1:208
	ds_write2_b32 v175, v106, v110 offset0:64 offset1:80
	ds_write2_b32 v175, v107, v111 offset0:192 offset1:208
	ds_write2_b32 v176, v92, v100 offset0:96 offset1:112
	ds_write2_b32 v176, v93, v101 offset0:224 offset1:240
	ds_write2_b32 v175, v94, v102 offset0:96 offset1:112
	ds_write2_b32 v175, v95, v103 offset0:224 offset1:240
	ds_write2_b32 v174, v24, v28 offset1:16
	ds_write2_b32 v174, v25, v29 offset0:128 offset1:144
	ds_write2_b32 v173, v26, v30 offset1:16
	ds_write2_b32 v173, v27, v31 offset0:128 offset1:144
	ds_write2_b32 v174, v16, v20 offset0:32 offset1:48
	ds_write2_b32 v174, v17, v21 offset0:160 offset1:176
	ds_write2_b32 v173, v18, v22 offset0:32 offset1:48
	ds_write2_b32 v173, v19, v23 offset0:160 offset1:176
	ds_write2_b32 v174, v56, v60 offset0:64 offset1:80
	ds_write2_b32 v174, v57, v61 offset0:192 offset1:208
	ds_write2_b32 v173, v58, v62 offset0:64 offset1:80
	ds_write2_b32 v173, v59, v63 offset0:192 offset1:208
	ds_write2_b32 v174, v44, v72 offset0:96 offset1:112
	ds_write2_b32 v174, v45, v73 offset0:224 offset1:240
	ds_write2_b32 v173, v46, v74 offset0:96 offset1:112
	ds_write2_b32 v173, v47, v75 offset0:224 offset1:240
	ds_write2_b32 v172, v8, v12 offset1:16
	ds_write2_b32 v172, v9, v13 offset0:128 offset1:144
	ds_write2_b32 v171, v10, v14 offset1:16
	ds_write2_b32 v171, v11, v15 offset0:128 offset1:144
	ds_write2_b32 v172, v0, v4 offset0:32 offset1:48
	ds_write2_b32 v172, v1, v5 offset0:160 offset1:176
	ds_write2_b32 v171, v2, v6 offset0:32 offset1:48
	ds_write2_b32 v171, v3, v7 offset0:160 offset1:176
	ds_write2_b32 v172, v48, v64 offset0:64 offset1:80
	ds_write2_b32 v172, v49, v65 offset0:192 offset1:208
	ds_write2_b32 v171, v50, v66 offset0:64 offset1:80
	ds_write2_b32 v171, v51, v67 offset0:192 offset1:208
	ds_write2_b32 v172, v68, v76 offset0:96 offset1:112
	ds_write2_b32 v172, v69, v77 offset0:224 offset1:240
	ds_write2_b32 v171, v70, v78 offset0:96 offset1:112
	ds_write2_b32 v171, v71, v79 offset0:224 offset1:240

.LBB0_1143:
	s_add_i32 s11, s10, 0x10000
	s_and_b32 s19, s11, 0x10000
	s_waitcnt vmcnt(0)
	s_barrier
	s_and_b32 s10, s10, 0x10000
	s_add_i32 s10, s10, 0
	v_add_u32_e32 v151, s10, v149
	v_add_u32_e32 v164, v151, v147
	ds_read_b128 v[152:155], v164
	ds_read_b128 v[156:159], v164 offset:2048
	ds_read_b128 v[160:163], v164 offset:4096
	ds_read_b128 v[164:167], v164 offset:6144
	v_add_u32_e32 v251, v151, v146
	v_add_u32_e32 v176, s10, v148
	v_add_u32_e32 v186, v176, v147
	ds_read_b128 v[168:171], v186 offset:32768
	ds_read_b128 v[172:175], v186 offset:34816
	ds_read_b128 v[178:181], v186 offset:36864
	ds_read_b128 v[182:185], v186 offset:38912
	v_add_u32_e32 v250, v176, v146
	v_add_u32_e32 v254, s19, v150
	v_add_u32_e32 v228, 0x2000, v254
	v_readfirstlane_b32 s19, v254
	v_lshl_add_u64 v[188:189], v[128:129], 0, s[2:3]
	s_waitcnt lgkmcnt(0)
	v_mfma_f32_16x16x32_bf16 v[124:127], v[152:155], v[168:171], v[124:127]
	ds_read_b128 v[212:215], v186 offset:40960
	v_mfma_f32_16x16x32_bf16 v[120:123], v[152:155], v[172:175], v[120:123]
	ds_read_b128 v[216:219], v186 offset:43008
	v_mfma_f32_16x16x32_bf16 v[116:119], v[152:155], v[178:181], v[116:119]
	ds_read_b128 v[220:223], v186 offset:45056
	v_mfma_f32_16x16x32_bf16 v[112:115], v[152:155], v[182:185], v[112:115]
	ds_read_b128 v[224:227], v186 offset:47104
	v_mfma_f32_16x16x32_bf16 v[104:107], v[156:159], v[168:171], v[104:107]
	ds_read_b128 v[192:195], v251
	v_mfma_f32_16x16x32_bf16 v[96:99], v[156:159], v[172:175], v[96:99]
	ds_read_b128 v[198:201], v251 offset:2048
	v_mfma_f32_16x16x32_bf16 v[88:91], v[156:159], v[178:181], v[88:91]
	ds_read_b128 v[204:207], v251 offset:4096
	v_mfma_f32_16x16x32_bf16 v[80:83], v[156:159], v[182:185], v[80:83]
	ds_read_b128 v[208:211], v251 offset:6144
	v_mfma_f32_16x16x32_bf16 v[72:75], v[160:163], v[168:171], v[72:75]
	s_mov_b32 m0, s19
	v_readfirstlane_b32 s19, v228
	v_mfma_f32_16x16x32_bf16 v[64:67], v[160:163], v[172:175], v[64:67]
	v_add_u32_e32 v228, 0x4000, v254
	global_load_lds_dwordx4 v[188:189], off
	v_mfma_f32_16x16x32_bf16 v[56:59], v[160:163], v[178:181], v[56:59]
	v_lshl_add_u64 v[188:189], v[130:131], 0, s[2:3]
	s_mov_b32 m0, s19
	v_mfma_f32_16x16x32_bf16 v[48:51], v[160:163], v[182:185], v[48:51]
	v_readfirstlane_b32 s19, v228
	v_add_u32_e32 v228, 0x6000, v254
	v_mfma_f32_16x16x32_bf16 v[40:43], v[164:167], v[168:171], v[40:43]
	global_load_lds_dwordx4 v[188:189], off
	v_lshl_add_u64 v[188:189], v[132:133], 0, s[2:3]
	v_mfma_f32_16x16x32_bf16 v[32:35], v[164:167], v[172:175], v[32:35]
	s_mov_b32 m0, s19
	v_readfirstlane_b32 s19, v228
	v_mfma_f32_16x16x32_bf16 v[24:27], v[164:167], v[178:181], v[24:27]
	global_load_lds_dwordx4 v[188:189], off
	v_lshl_add_u64 v[188:189], v[134:135], 0, s[2:3]
	v_mfma_f32_16x16x32_bf16 v[16:19], v[164:167], v[182:185], v[16:19]
	s_mov_b32 m0, s19
	v_add_u32_e32 v253, 0x8000, v254
	s_waitcnt lgkmcnt(4)
	v_mfma_f32_16x16x32_bf16 v[100:103], v[152:155], v[212:215], v[100:103]
	global_load_lds_dwordx4 v[188:189], off
	v_lshl_add_u64 v[188:189], v[136:137], 0, s[2:3]
	v_mfma_f32_16x16x32_bf16 v[92:95], v[152:155], v[216:219], v[92:95]
	s_mov_b64 s[20:21], 0x1320080
	v_readfirstlane_b32 s19, v253
	v_mfma_f32_16x16x32_bf16 v[84:87], v[152:155], v[220:223], v[84:87]
	ds_read_b128 v[168:171], v250 offset:32768
	v_add_u32_e32 v253, 0xa000, v254
	v_lshl_add_u64 v[228:229], v[188:189], 0, s[20:21]
	v_mfma_f32_16x16x32_bf16 v[76:79], v[152:155], v[224:227], v[76:79]
	ds_read_b128 v[172:175], v250 offset:34816
	s_mov_b32 m0, s19
	s_mov_b64 s[20:21], 0x1378080
	v_mfma_f32_16x16x32_bf16 v[68:71], v[156:159], v[212:215], v[68:71]
	ds_read_b128 v[178:181], v250 offset:36864
	v_readfirstlane_b32 s19, v253
	v_add_u32_e32 v253, 0xc000, v254
	v_mfma_f32_16x16x32_bf16 v[60:63], v[156:159], v[216:219], v[60:63]
	ds_read_b128 v[182:185], v250 offset:38912
	global_load_lds_dwordx4 v[228:229], off
	v_lshl_add_u64 v[228:229], v[188:189], 0, s[20:21]
	v_mfma_f32_16x16x32_bf16 v[52:55], v[156:159], v[220:223], v[52:55]
	s_mov_b32 m0, s19
	s_mov_b64 s[20:21], 0x13d0080
	v_mfma_f32_16x16x32_bf16 v[44:47], v[156:159], v[224:227], v[44:47]
	v_readfirstlane_b32 s19, v253
	v_add_u32_e32 v254, 0xe000, v254
	v_mfma_f32_16x16x32_bf16 v[36:39], v[160:163], v[212:215], v[36:39]
	global_load_lds_dwordx4 v[228:229], off
	v_lshl_add_u64 v[228:229], v[188:189], 0, s[20:21]
	v_mfma_f32_16x16x32_bf16 v[28:31], v[160:163], v[216:219], v[28:31]
	s_mov_b32 m0, s19
	s_mov_b64 s[20:21], 0x1428080
	v_mfma_f32_16x16x32_bf16 v[20:23], v[160:163], v[220:223], v[20:23]
	v_readfirstlane_b32 s19, v254
	global_load_lds_dwordx4 v[228:229], off
	v_mfma_f32_16x16x32_bf16 v[12:15], v[160:163], v[224:227], v[12:15]
	v_lshl_add_u64 v[188:189], v[188:189], 0, s[20:21]
	s_mov_b32 m0, s19
	v_mfma_f32_16x16x32_bf16 v[8:11], v[164:167], v[212:215], v[8:11]
	global_load_lds_dwordx4 v[188:189], off
	v_mfma_f32_16x16x32_bf16 v[4:7], v[164:167], v[216:219], v[4:7]
	v_mfma_f32_16x16x32_bf16 v[0:3], v[164:167], v[220:223], v[0:3]
	v_mfma_f32_16x16x32_bf16 v[108:111], v[164:167], v[224:227], v[108:111]
	s_waitcnt lgkmcnt(0)
	v_mfma_f32_16x16x32_bf16 v[124:127], v[192:195], v[168:171], v[124:127]
	ds_read_b128 v[212:215], v250 offset:40960
	v_mfma_f32_16x16x32_bf16 v[120:123], v[192:195], v[172:175], v[120:123]
	ds_read_b128 v[216:219], v250 offset:43008
	v_mfma_f32_16x16x32_bf16 v[116:119], v[192:195], v[178:181], v[116:119]
	ds_read_b128 v[220:223], v250 offset:45056
	v_mfma_f32_16x16x32_bf16 v[112:115], v[192:195], v[182:185], v[112:115]
	ds_read_b128 v[224:227], v250 offset:47104
	v_mfma_f32_16x16x32_bf16 v[104:107], v[198:201], v[168:171], v[104:107]
	v_mfma_f32_16x16x32_bf16 v[96:99], v[198:201], v[172:175], v[96:99]
	v_mfma_f32_16x16x32_bf16 v[88:91], v[198:201], v[178:181], v[88:91]
	v_mfma_f32_16x16x32_bf16 v[80:83], v[198:201], v[182:185], v[80:83]
	v_mfma_f32_16x16x32_bf16 v[72:75], v[204:207], v[168:171], v[72:75]
	v_mfma_f32_16x16x32_bf16 v[64:67], v[204:207], v[172:175], v[64:67]
	v_mfma_f32_16x16x32_bf16 v[56:59], v[204:207], v[178:181], v[56:59]
	v_mfma_f32_16x16x32_bf16 v[48:51], v[204:207], v[182:185], v[48:51]
	v_mfma_f32_16x16x32_bf16 v[40:43], v[208:211], v[168:171], v[40:43]
	v_mfma_f32_16x16x32_bf16 v[32:35], v[208:211], v[172:175], v[32:35]
	v_mfma_f32_16x16x32_bf16 v[24:27], v[208:211], v[178:181], v[24:27]
	v_mfma_f32_16x16x32_bf16 v[16:19], v[208:211], v[182:185], v[16:19]
	s_waitcnt lgkmcnt(0)
	v_mfma_f32_16x16x32_bf16 v[100:103], v[192:195], v[212:215], v[100:103]
	v_mfma_f32_16x16x32_bf16 v[92:95], v[192:195], v[216:219], v[92:95]
	v_mfma_f32_16x16x32_bf16 v[84:87], v[192:195], v[220:223], v[84:87]
	v_mfma_f32_16x16x32_bf16 v[76:79], v[192:195], v[224:227], v[76:79]
	v_mfma_f32_16x16x32_bf16 v[68:71], v[198:201], v[212:215], v[68:71]
	v_mfma_f32_16x16x32_bf16 v[60:63], v[198:201], v[216:219], v[60:63]
	v_mfma_f32_16x16x32_bf16 v[52:55], v[198:201], v[220:223], v[52:55]
	v_mfma_f32_16x16x32_bf16 v[44:47], v[198:201], v[224:227], v[44:47]
	v_mfma_f32_16x16x32_bf16 v[36:39], v[204:207], v[212:215], v[36:39]
	v_mfma_f32_16x16x32_bf16 v[28:31], v[204:207], v[216:219], v[28:31]
	v_mfma_f32_16x16x32_bf16 v[20:23], v[204:207], v[220:223], v[20:23]
	v_mfma_f32_16x16x32_bf16 v[12:15], v[204:207], v[224:227], v[12:15]
	s_add_u32 s2, s2, 0x80
	s_addc_u32 s3, s3, 0
	s_cmpk_eq_i32 s2, 0x1580
	s_mov_b32 s10, s11
	v_mfma_f32_16x16x32_bf16 v[8:11], v[208:211], v[212:215], v[8:11]
	v_mfma_f32_16x16x32_bf16 v[4:7], v[208:211], v[216:219], v[4:7]
	v_mfma_f32_16x16x32_bf16 v[0:3], v[208:211], v[220:223], v[0:3]
	v_mfma_f32_16x16x32_bf16 v[108:111], v[208:211], v[224:227], v[108:111]
	s_cbranch_scc0 .LBB0_1143
	s_add_i32 s2, 0, 0x10000
	v_add_u32_e32 v136, s2, v149
	v_add_u32_e32 v137, v136, v147
	s_waitcnt vmcnt(0)
	s_barrier
	ds_read_b128 v[128:131], v137
	ds_read_b128 v[132:135], v137 offset:2048
	ds_read_b128 v[150:153], v137 offset:4096
	ds_read_b128 v[154:157], v137 offset:6144
	v_add_u32_e32 v137, s2, v148
	v_add_u32_e32 v147, v137, v147
	ds_read_b128 v[158:161], v147 offset:32768
	ds_read_b128 v[162:165], v147 offset:34816
	ds_read_b128 v[166:169], v147 offset:36864
	ds_read_b128 v[170:173], v147 offset:38912
	s_waitcnt lgkmcnt(0)
	v_mfma_f32_16x16x32_bf16 v[124:127], v[128:131], v[158:161], v[124:127]
	v_mfma_f32_16x16x32_bf16 v[120:123], v[128:131], v[162:165], v[120:123]
	v_mfma_f32_16x16x32_bf16 v[116:119], v[128:131], v[166:169], v[116:119]
	v_mfma_f32_16x16x32_bf16 v[112:115], v[128:131], v[170:173], v[112:115]
	v_mfma_f32_16x16x32_bf16 v[104:107], v[132:135], v[158:161], v[104:107]
	v_mfma_f32_16x16x32_bf16 v[72:75], v[150:153], v[158:161], v[72:75]
	v_mfma_f32_16x16x32_bf16 v[64:67], v[150:153], v[162:165], v[64:67]
	v_mfma_f32_16x16x32_bf16 v[56:59], v[150:153], v[166:169], v[56:59]
	v_mfma_f32_16x16x32_bf16 v[48:51], v[150:153], v[170:173], v[48:51]
	v_mfma_f32_16x16x32_bf16 v[178:181], v[132:135], v[162:165], v[96:99]
	v_mfma_f32_16x16x32_bf16 v[182:185], v[132:135], v[166:169], v[88:91]
	v_mfma_f32_16x16x32_bf16 v[186:189], v[132:135], v[170:173], v[80:83]
	v_mfma_f32_16x16x32_bf16 v[158:161], v[154:157], v[158:161], v[40:43]
	v_mfma_f32_16x16x32_bf16 v[162:165], v[154:157], v[162:165], v[32:35]
	v_mfma_f32_16x16x32_bf16 v[166:169], v[154:157], v[166:169], v[24:27]
	v_mfma_f32_16x16x32_bf16 v[170:173], v[154:157], v[170:173], v[16:19]
	s_nop 2
	ds_read_b128 v[16:19], v147 offset:40960
	ds_read_b128 v[24:27], v147 offset:43008
	ds_read_b128 v[32:35], v147 offset:45056
	ds_read_b128 v[40:43], v147 offset:47104
	s_waitcnt lgkmcnt(0)
	v_mfma_f32_16x16x32_bf16 v[100:103], v[128:131], v[16:19], v[100:103]
	v_mfma_f32_16x16x32_bf16 v[92:95], v[128:131], v[24:27], v[92:95]
	v_mfma_f32_16x16x32_bf16 v[192:195], v[128:131], v[32:35], v[84:87]
	v_mfma_f32_16x16x32_bf16 v[76:79], v[128:131], v[40:43], v[76:79]
	v_mfma_f32_16x16x32_bf16 v[68:71], v[132:135], v[16:19], v[68:71]
	v_mfma_f32_16x16x32_bf16 v[60:63], v[132:135], v[24:27], v[60:63]
	v_mfma_f32_16x16x32_bf16 v[128:131], v[132:135], v[32:35], v[52:55]
	v_mfma_f32_16x16x32_bf16 v[44:47], v[132:135], v[40:43], v[44:47]
	v_mfma_f32_16x16x32_bf16 v[132:135], v[150:153], v[16:19], v[36:39]
	v_mfma_f32_16x16x32_bf16 v[198:201], v[150:153], v[24:27], v[28:31]
	v_mfma_f32_16x16x32_bf16 v[204:207], v[150:153], v[32:35], v[20:23]
	v_mfma_f32_16x16x32_bf16 v[148:151], v[150:153], v[40:43], v[12:15]
	v_mfma_f32_16x16x32_bf16 v[208:211], v[154:157], v[16:19], v[8:11]
	v_mfma_f32_16x16x32_bf16 v[212:215], v[154:157], v[24:27], v[4:7]
	v_mfma_f32_16x16x32_bf16 v[216:219], v[154:157], v[32:35], v[0:3]
	v_mfma_f32_16x16x32_bf16 v[154:157], v[154:157], v[40:43], v[108:111]
	s_nop 1
	v_add_u32_e32 v0, v136, v146
	v_add_u32_e32 v136, v137, v146
	ds_read_b128 v[108:111], v0
	ds_read_b128 v[220:223], v0 offset:2048
	ds_read_b128 v[224:227], v0 offset:4096
	ds_read_b128 v[228:231], v0 offset:6144
	ds_read_b128 v[0:3], v136 offset:32768
	ds_read_b128 v[4:7], v136 offset:34816
	ds_read_b128 v[232:235], v136 offset:36864
	ds_read_b128 v[236:239], v136 offset:38912
	s_waitcnt lgkmcnt(0)
	v_mfma_f32_16x16x32_bf16 v[88:91], v[108:111], v[0:3], v[124:127]
	v_mfma_f32_16x16x32_bf16 v[96:99], v[108:111], v[4:7], v[120:123]
	v_mfma_f32_16x16x32_bf16 v[80:83], v[108:111], v[232:235], v[116:119]
	v_mfma_f32_16x16x32_bf16 v[84:87], v[108:111], v[236:239], v[112:115]
	v_mfma_f32_16x16x32_bf16 v[40:43], v[220:223], v[0:3], v[104:107]
	v_mfma_f32_16x16x32_bf16 v[52:55], v[220:223], v[4:7], v[178:181]
	v_mfma_f32_16x16x32_bf16 v[32:35], v[220:223], v[232:235], v[182:185]
	v_mfma_f32_16x16x32_bf16 v[36:39], v[220:223], v[236:239], v[186:189]
	v_mfma_f32_16x16x32_bf16 v[24:27], v[224:227], v[0:3], v[72:75]
	v_mfma_f32_16x16x32_bf16 v[28:31], v[224:227], v[4:7], v[64:67]
	v_mfma_f32_16x16x32_bf16 v[16:19], v[224:227], v[232:235], v[56:59]
	v_mfma_f32_16x16x32_bf16 v[20:23], v[224:227], v[236:239], v[48:51]
	v_mfma_f32_16x16x32_bf16 v[8:11], v[228:231], v[0:3], v[158:161]
	v_mfma_f32_16x16x32_bf16 v[12:15], v[228:231], v[4:7], v[162:165]
	v_mfma_f32_16x16x32_bf16 v[0:3], v[228:231], v[232:235], v[166:169]
	v_mfma_f32_16x16x32_bf16 v[4:7], v[228:231], v[236:239], v[170:173]
	ds_read_b128 v[48:51], v136 offset:40960
	ds_read_b128 v[64:67], v136 offset:43008
	ds_read_b128 v[158:161], v136 offset:45056
	ds_read_b128 v[162:165], v136 offset:47104
	s_waitcnt lgkmcnt(0)
	v_mfma_f32_16x16x32_bf16 v[104:107], v[220:223], v[48:51], v[68:71]
	v_cmp_ne_u32_e32 vcc, 0, v138
	v_cmp_eq_u32_e64 s[2:3], 0, v138
	s_waitcnt vmcnt(0)
	v_lshl_or_b32 v68, v140, 2, v141
	v_lshl_add_u32 v69, v139, 2, 0
	v_mfma_f32_16x16x32_bf16 v[120:123], v[108:111], v[48:51], v[100:103]
	v_lshl_add_u32 v152, v68, 9, v69
	v_add_u32_e32 v153, 0x400, v152
	v_add_u32_e32 v147, 0x6000, v152
	v_mfma_f32_16x16x32_bf16 v[124:127], v[108:111], v[64:67], v[92:95]
	v_add_u32_e32 v146, 0x6400, v152
	s_barrier
	v_mfma_f32_16x16x32_bf16 v[112:115], v[108:111], v[158:161], v[192:195]
	v_mfma_f32_16x16x32_bf16 v[116:119], v[108:111], v[162:165], v[76:79]
	v_mfma_f32_16x16x32_bf16 v[108:111], v[220:223], v[64:67], v[60:63]
	v_mfma_f32_16x16x32_bf16 v[92:95], v[220:223], v[158:161], v[128:131]
	v_mfma_f32_16x16x32_bf16 v[100:103], v[220:223], v[162:165], v[44:47]
	v_mfma_f32_16x16x32_bf16 v[56:59], v[224:227], v[48:51], v[132:135]
	v_mfma_f32_16x16x32_bf16 v[60:63], v[224:227], v[64:67], v[198:201]
	v_mfma_f32_16x16x32_bf16 v[44:47], v[224:227], v[158:161], v[204:207]
	v_mfma_f32_16x16x32_bf16 v[72:75], v[224:227], v[162:165], v[148:151]
	v_mfma_f32_16x16x32_bf16 v[48:51], v[228:231], v[48:51], v[208:211]
	s_nop 1
	v_add_u32_e32 v151, 0x2000, v152
	v_add_u32_e32 v150, 0x2400, v152
	v_add_u32_e32 v149, 0x4000, v152
	v_mfma_f32_16x16x32_bf16 v[64:67], v[228:231], v[64:67], v[212:215]
	v_add_u32_e32 v148, 0x4400, v152
	v_mfma_f32_16x16x32_bf16 v[68:71], v[228:231], v[158:161], v[216:219]
	v_mfma_f32_16x16x32_bf16 v[76:79], v[228:231], v[162:165], v[154:157]
	s_and_saveexec_b64 s[10:11], s[2:3]
	s_cbranch_execz .LBB0_1146
	ds_write2_b32 v152, v88, v96 offset1:16
	ds_write2_b32 v152, v89, v97 offset0:128 offset1:144
	ds_write2_b32 v153, v90, v98 offset1:16
	ds_write2_b32 v153, v91, v99 offset0:128 offset1:144
	ds_write2_b32 v152, v80, v84 offset0:32 offset1:48
	ds_write2_b32 v152, v81, v85 offset0:160 offset1:176
	ds_write2_b32 v153, v82, v86 offset0:32 offset1:48
	ds_write2_b32 v153, v83, v87 offset0:160 offset1:176
	ds_write2_b32 v152, v120, v124 offset0:64 offset1:80
	ds_write2_b32 v152, v121, v125 offset0:192 offset1:208
	ds_write2_b32 v153, v122, v126 offset0:64 offset1:80
	ds_write2_b32 v153, v123, v127 offset0:192 offset1:208
	ds_write2_b32 v152, v112, v116 offset0:96 offset1:112
	ds_write2_b32 v152, v113, v117 offset0:224 offset1:240
	ds_write2_b32 v153, v114, v118 offset0:96 offset1:112
	ds_write2_b32 v153, v115, v119 offset0:224 offset1:240
	ds_write2_b32 v151, v40, v52 offset1:16
	ds_write2_b32 v151, v41, v53 offset0:128 offset1:144
	ds_write2_b32 v150, v42, v54 offset1:16
	ds_write2_b32 v150, v43, v55 offset0:128 offset1:144
	ds_write2_b32 v151, v32, v36 offset0:32 offset1:48
	ds_write2_b32 v151, v33, v37 offset0:160 offset1:176
	ds_write2_b32 v150, v34, v38 offset0:32 offset1:48
	ds_write2_b32 v150, v35, v39 offset0:160 offset1:176
	ds_write2_b32 v151, v104, v108 offset0:64 offset1:80
	ds_write2_b32 v151, v105, v109 offset0:192 offset1:208
	ds_write2_b32 v150, v106, v110 offset0:64 offset1:80
	ds_write2_b32 v150, v107, v111 offset0:192 offset1:208
	ds_write2_b32 v151, v92, v100 offset0:96 offset1:112
	ds_write2_b32 v151, v93, v101 offset0:224 offset1:240
	ds_write2_b32 v150, v94, v102 offset0:96 offset1:112
	ds_write2_b32 v150, v95, v103 offset0:224 offset1:240
	ds_write2_b32 v149, v24, v28 offset1:16
	ds_write2_b32 v149, v25, v29 offset0:128 offset1:144
	ds_write2_b32 v148, v26, v30 offset1:16
	ds_write2_b32 v148, v27, v31 offset0:128 offset1:144
	ds_write2_b32 v149, v16, v20 offset0:32 offset1:48
	ds_write2_b32 v149, v17, v21 offset0:160 offset1:176
	ds_write2_b32 v148, v18, v22 offset0:32 offset1:48
	ds_write2_b32 v148, v19, v23 offset0:160 offset1:176
	ds_write2_b32 v149, v56, v60 offset0:64 offset1:80
	ds_write2_b32 v149, v57, v61 offset0:192 offset1:208
	ds_write2_b32 v148, v58, v62 offset0:64 offset1:80
	ds_write2_b32 v148, v59, v63 offset0:192 offset1:208
	ds_write2_b32 v149, v44, v72 offset0:96 offset1:112
	ds_write2_b32 v149, v45, v73 offset0:224 offset1:240
	ds_write2_b32 v148, v46, v74 offset0:96 offset1:112
	ds_write2_b32 v148, v47, v75 offset0:224 offset1:240
	ds_write2_b32 v147, v8, v12 offset1:16
	ds_write2_b32 v147, v9, v13 offset0:128 offset1:144
	ds_write2_b32 v146, v10, v14 offset1:16
	ds_write2_b32 v146, v11, v15 offset0:128 offset1:144
	ds_write2_b32 v147, v0, v4 offset0:32 offset1:48
	ds_write2_b32 v147, v1, v5 offset0:160 offset1:176
	ds_write2_b32 v146, v2, v6 offset0:32 offset1:48
	ds_write2_b32 v146, v3, v7 offset0:160 offset1:176
	ds_write2_b32 v147, v48, v64 offset0:64 offset1:80
	ds_write2_b32 v147, v49, v65 offset0:192 offset1:208
	ds_write2_b32 v146, v50, v66 offset0:64 offset1:80
	ds_write2_b32 v146, v51, v67 offset0:192 offset1:208
	ds_write2_b32 v147, v68, v76 offset0:96 offset1:112
	ds_write2_b32 v147, v69, v77 offset0:224 offset1:240
	ds_write2_b32 v146, v70, v78 offset0:96 offset1:112
	ds_write2_b32 v146, v71, v79 offset0:224 offset1:240
